# FF1 hidden-activation stores marked non-temporal (streamed out of L2 before the barrier write-back)
# baseline (speedup 1.0000x reference)
.LBB0_1396:
	ds_read_b128 v[150:153], v145
	ds_read_b128 v[154:157], v145 offset:1024
	ds_read_b128 v[158:161], v145 offset:2048
	ds_read_b128 v[162:165], v145 offset:3072
	s_add_u32 s33, s34, 0xfffc0080
	s_addc_u32 s36, s35, -1
	s_cmp_eq_u32 s71, 12
	s_cselect_b32 s41, s25, s36
	s_cselect_b32 s40, s67, s33
	s_cselect_b32 s37, s23, s70
	s_cselect_b32 s36, s68, s69
	v_lshl_add_u64 v[206:207], s[34:35], 0, v[136:137]
	s_add_i32 m0, s54, 0xc000
	ds_read_b128 v[166:169], v146
	ds_read_b128 v[178:181], v146 offset:1024
	ds_read_b128 v[182:185], v146 offset:2048
	ds_read_b128 v[186:189], v146 offset:3072
	ds_read_b128 v[190:193], v146 offset:4096
	ds_read_b128 v[194:197], v146 offset:5120
	ds_read_b128 v[198:201], v146 offset:6144
	ds_read_b128 v[202:205], v146 offset:7168
	global_load_lds_dwordx4 v[206:207], off
	v_lshl_add_u64 v[206:207], s[34:35], 0, v[134:135]
	s_add_i32 m0, s54, 0xe000
	s_nop 0
	global_load_lds_dwordx4 v[206:207], off
	s_waitcnt lgkmcnt(8)
	s_barrier
	s_waitcnt lgkmcnt(0)
	s_setprio 1
	s_waitcnt lgkmcnt(0)
	v_mfma_f32_16x16x32_bf16 v[124:127], v[150:153], v[166:169], v[124:127]
	v_mfma_f32_16x16x32_bf16 v[120:123], v[158:161], v[166:169], v[120:123]
	v_mfma_f32_16x16x32_bf16 v[116:119], v[150:153], v[182:185], v[116:119]
	v_mfma_f32_16x16x32_bf16 v[112:115], v[158:161], v[182:185], v[112:115]
	v_mfma_f32_16x16x32_bf16 v[108:111], v[150:153], v[190:193], v[108:111]
	v_mfma_f32_16x16x32_bf16 v[104:107], v[158:161], v[190:193], v[104:107]
	v_mfma_f32_16x16x32_bf16 v[100:103], v[150:153], v[198:201], v[100:103]
	v_mfma_f32_16x16x32_bf16 v[96:99], v[158:161], v[198:201], v[96:99]
	v_mfma_f32_16x16x32_bf16 v[124:127], v[154:157], v[178:181], v[124:127]
	v_mfma_f32_16x16x32_bf16 v[120:123], v[162:165], v[178:181], v[120:123]
	v_mfma_f32_16x16x32_bf16 v[116:119], v[154:157], v[186:189], v[116:119]
	v_mfma_f32_16x16x32_bf16 v[112:115], v[162:165], v[186:189], v[112:115]
	v_mfma_f32_16x16x32_bf16 v[108:111], v[154:157], v[194:197], v[108:111]
	v_mfma_f32_16x16x32_bf16 v[104:107], v[162:165], v[194:197], v[104:107]
	v_mfma_f32_16x16x32_bf16 v[100:103], v[154:157], v[202:205], v[100:103]
	v_mfma_f32_16x16x32_bf16 v[96:99], v[162:165], v[202:205], v[96:99]
	s_setprio 0
	s_barrier
	s_add_i32 s33, s65, s53
	v_lshl_add_u64 v[222:223], s[36:37], 0, v[130:131]
	s_mov_b32 m0, s33
	ds_read_b128 v[206:209], v147
	ds_read_b128 v[210:213], v147 offset:1024
	ds_read_b128 v[214:217], v147 offset:2048
	ds_read_b128 v[218:221], v147 offset:3072
	global_load_lds_dwordx4 v[222:223], off
	v_lshl_add_u64 v[224:225], s[36:37], 0, v[128:129]
	s_add_i32 m0, s33, 0x2000
	s_nop 0
	global_load_lds_dwordx4 v[224:225], off
	s_barrier
	s_waitcnt lgkmcnt(0)
	s_setprio 1
	s_waitcnt lgkmcnt(0)
	v_mfma_f32_16x16x32_bf16 v[92:95], v[206:209], v[166:169], v[92:95]
	v_mfma_f32_16x16x32_bf16 v[88:91], v[214:217], v[166:169], v[88:91]
	v_mfma_f32_16x16x32_bf16 v[84:87], v[206:209], v[182:185], v[84:87]
	v_mfma_f32_16x16x32_bf16 v[80:83], v[214:217], v[182:185], v[80:83]
	v_mfma_f32_16x16x32_bf16 v[76:79], v[206:209], v[190:193], v[76:79]
	v_mfma_f32_16x16x32_bf16 v[72:75], v[214:217], v[190:193], v[72:75]
	v_mfma_f32_16x16x32_bf16 v[68:71], v[206:209], v[198:201], v[68:71]
	v_mfma_f32_16x16x32_bf16 v[64:67], v[214:217], v[198:201], v[64:67]
	v_mfma_f32_16x16x32_bf16 v[92:95], v[210:213], v[178:181], v[92:95]
	v_mfma_f32_16x16x32_bf16 v[88:91], v[218:221], v[178:181], v[88:91]
	v_mfma_f32_16x16x32_bf16 v[84:87], v[210:213], v[186:189], v[84:87]
	v_mfma_f32_16x16x32_bf16 v[80:83], v[218:221], v[186:189], v[80:83]
	v_mfma_f32_16x16x32_bf16 v[76:79], v[210:213], v[194:197], v[76:79]
	v_mfma_f32_16x16x32_bf16 v[72:75], v[218:221], v[194:197], v[72:75]
	v_mfma_f32_16x16x32_bf16 v[68:71], v[210:213], v[202:205], v[68:71]
	v_mfma_f32_16x16x32_bf16 v[64:67], v[218:221], v[202:205], v[64:67]
	s_setprio 0
	s_mov_b32 m0, s54
	v_lshl_add_u64 v[226:227], s[40:41], 0, v[130:131]
	s_barrier
	ds_read_b128 v[166:169], v146 offset:16384
	ds_read_b128 v[178:181], v146 offset:17408
	ds_read_b128 v[182:185], v146 offset:18432
	ds_read_b128 v[186:189], v146 offset:19456
	ds_read_b128 v[190:193], v146 offset:20480
	ds_read_b128 v[194:197], v146 offset:21504
	ds_read_b128 v[198:201], v146 offset:22528
	ds_read_b128 v[202:205], v146 offset:23552
	global_load_lds_dwordx4 v[226:227], off
	v_lshl_add_u64 v[228:229], s[40:41], 0, v[128:129]
	s_mov_b32 m0, s55
	s_nop 0
	global_load_lds_dwordx4 v[228:229], off
	s_barrier
	s_waitcnt lgkmcnt(0)
	s_setprio 1
	s_waitcnt lgkmcnt(0)
	v_mfma_f32_16x16x32_bf16 v[60:63], v[150:153], v[166:169], v[60:63]
	v_mfma_f32_16x16x32_bf16 v[56:59], v[158:161], v[166:169], v[56:59]
	v_mfma_f32_16x16x32_bf16 v[52:55], v[150:153], v[182:185], v[52:55]
	v_mfma_f32_16x16x32_bf16 v[48:51], v[158:161], v[182:185], v[48:51]
	v_mfma_f32_16x16x32_bf16 v[44:47], v[150:153], v[190:193], v[44:47]
	v_mfma_f32_16x16x32_bf16 v[40:43], v[158:161], v[190:193], v[40:43]
	v_mfma_f32_16x16x32_bf16 v[36:39], v[150:153], v[198:201], v[36:39]
	v_mfma_f32_16x16x32_bf16 v[32:35], v[158:161], v[198:201], v[32:35]
	v_mfma_f32_16x16x32_bf16 v[60:63], v[154:157], v[178:181], v[60:63]
	v_mfma_f32_16x16x32_bf16 v[56:59], v[162:165], v[178:181], v[56:59]
	v_mfma_f32_16x16x32_bf16 v[52:55], v[154:157], v[186:189], v[52:55]
	v_mfma_f32_16x16x32_bf16 v[48:51], v[162:165], v[186:189], v[48:51]
	v_mfma_f32_16x16x32_bf16 v[44:47], v[154:157], v[194:197], v[44:47]
	v_mfma_f32_16x16x32_bf16 v[40:43], v[162:165], v[194:197], v[40:43]
	v_mfma_f32_16x16x32_bf16 v[36:39], v[154:157], v[202:205], v[36:39]
	v_mfma_f32_16x16x32_bf16 v[32:35], v[162:165], v[202:205], v[32:35]
	s_setprio 0
	s_barrier
	s_add_u32 s72, s36, 0x40000
	s_addc_u32 s73, s37, 0
	s_add_i32 s33, s66, s53
	v_lshl_add_u64 v[150:151], s[72:73], 0, v[130:131]
	s_mov_b32 m0, s33
	s_nop 0
	global_load_lds_dwordx4 v[150:151], off
	v_lshl_add_u64 v[150:151], s[72:73], 0, v[128:129]
	s_add_i32 m0, s33, 0x2000
	s_nop 0
	global_load_lds_dwordx4 v[150:151], off
	s_waitcnt vmcnt(6)
	s_barrier
	s_setprio 1
	v_mfma_f32_16x16x32_bf16 v[28:31], v[206:209], v[166:169], v[28:31]
	v_mfma_f32_16x16x32_bf16 v[24:27], v[214:217], v[166:169], v[24:27]
	v_mfma_f32_16x16x32_bf16 v[20:23], v[206:209], v[182:185], v[20:23]
	v_mfma_f32_16x16x32_bf16 v[16:19], v[214:217], v[182:185], v[16:19]
	v_mfma_f32_16x16x32_bf16 v[12:15], v[206:209], v[190:193], v[12:15]
	v_mfma_f32_16x16x32_bf16 v[8:11], v[214:217], v[190:193], v[8:11]
	v_mfma_f32_16x16x32_bf16 v[4:7], v[206:209], v[198:201], v[4:7]
	v_mfma_f32_16x16x32_bf16 v[0:3], v[214:217], v[198:201], v[0:3]
	v_mfma_f32_16x16x32_bf16 v[28:31], v[210:213], v[178:181], v[28:31]
	v_mfma_f32_16x16x32_bf16 v[24:27], v[218:221], v[178:181], v[24:27]
	v_mfma_f32_16x16x32_bf16 v[20:23], v[210:213], v[186:189], v[20:23]
	v_mfma_f32_16x16x32_bf16 v[16:19], v[218:221], v[186:189], v[16:19]
	v_mfma_f32_16x16x32_bf16 v[12:15], v[210:213], v[194:197], v[12:15]
	v_mfma_f32_16x16x32_bf16 v[8:11], v[218:221], v[194:197], v[8:11]
	v_mfma_f32_16x16x32_bf16 v[4:7], v[210:213], v[202:205], v[4:7]
	v_mfma_f32_16x16x32_bf16 v[0:3], v[218:221], v[202:205], v[0:3]
	s_setprio 0
	s_add_i32 s33, 0, 0x18000
	v_add_u32_e32 v132, s33, v143
	s_barrier
	ds_read_b128 v[150:153], v132
	ds_read_b128 v[154:157], v132 offset:1024
	ds_read_b128 v[158:161], v132 offset:2048
	ds_read_b128 v[162:165], v132 offset:3072
	s_add_u32 s40, s40, 0x40000
	s_addc_u32 s41, s41, 0
	s_mov_b32 m0, s56
	v_lshl_add_u64 v[206:207], s[40:41], 0, v[130:131]
	ds_read_b128 v[166:169], v146 offset:32768
	ds_read_b128 v[178:181], v146 offset:33792
	ds_read_b128 v[182:185], v146 offset:34816
	ds_read_b128 v[186:189], v146 offset:35840
	ds_read_b128 v[190:193], v146 offset:36864
	ds_read_b128 v[194:197], v146 offset:37888
	ds_read_b128 v[198:201], v146 offset:38912
	ds_read_b128 v[202:205], v146 offset:39936
	global_load_lds_dwordx4 v[206:207], off
	v_lshl_add_u64 v[206:207], s[40:41], 0, v[128:129]
	s_mov_b32 m0, s57
	s_nop 0
	global_load_lds_dwordx4 v[206:207], off
	s_waitcnt lgkmcnt(8)
	s_barrier
	s_waitcnt lgkmcnt(0)
	s_setprio 1
	s_waitcnt lgkmcnt(0)
	v_mfma_f32_16x16x32_bf16 v[124:127], v[150:153], v[166:169], v[124:127]
	v_mfma_f32_16x16x32_bf16 v[120:123], v[158:161], v[166:169], v[120:123]
	v_mfma_f32_16x16x32_bf16 v[116:119], v[150:153], v[182:185], v[116:119]
	v_mfma_f32_16x16x32_bf16 v[112:115], v[158:161], v[182:185], v[112:115]
	v_mfma_f32_16x16x32_bf16 v[108:111], v[150:153], v[190:193], v[108:111]
	v_mfma_f32_16x16x32_bf16 v[104:107], v[158:161], v[190:193], v[104:107]
	v_mfma_f32_16x16x32_bf16 v[100:103], v[150:153], v[198:201], v[100:103]
	v_mfma_f32_16x16x32_bf16 v[96:99], v[158:161], v[198:201], v[96:99]
	v_mfma_f32_16x16x32_bf16 v[124:127], v[154:157], v[178:181], v[124:127]
	v_mfma_f32_16x16x32_bf16 v[120:123], v[162:165], v[178:181], v[120:123]
	v_mfma_f32_16x16x32_bf16 v[116:119], v[154:157], v[186:189], v[116:119]
	v_mfma_f32_16x16x32_bf16 v[112:115], v[162:165], v[186:189], v[112:115]
	v_mfma_f32_16x16x32_bf16 v[108:111], v[154:157], v[194:197], v[108:111]
	v_mfma_f32_16x16x32_bf16 v[104:107], v[162:165], v[194:197], v[104:107]
	v_mfma_f32_16x16x32_bf16 v[100:103], v[154:157], v[202:205], v[100:103]
	v_mfma_f32_16x16x32_bf16 v[96:99], v[162:165], v[202:205], v[96:99]
	s_setprio 0
	s_barrier
	s_add_i32 s40, 0, 0x1c000
	s_add_i32 s33, s33, s53
	v_add_u32_e32 v132, s40, v143
	v_lshl_add_u64 v[222:223], v[222:223], 0, s[12:13]
	s_mov_b32 m0, s33
	ds_read_b128 v[206:209], v132
	ds_read_b128 v[210:213], v132 offset:1024
	ds_read_b128 v[214:217], v132 offset:2048
	ds_read_b128 v[218:221], v132 offset:3072
	global_load_lds_dwordx4 v[222:223], off
	v_lshl_add_u64 v[222:223], v[224:225], 0, s[12:13]
	s_add_i32 m0, s33, 0x2000
	s_nop 0
	global_load_lds_dwordx4 v[222:223], off
	s_barrier
	s_waitcnt lgkmcnt(0)
	s_setprio 1
	s_waitcnt lgkmcnt(0)
	v_mfma_f32_16x16x32_bf16 v[92:95], v[206:209], v[166:169], v[92:95]
	v_mfma_f32_16x16x32_bf16 v[88:91], v[214:217], v[166:169], v[88:91]
	v_mfma_f32_16x16x32_bf16 v[84:87], v[206:209], v[182:185], v[84:87]
	v_mfma_f32_16x16x32_bf16 v[80:83], v[214:217], v[182:185], v[80:83]
	v_mfma_f32_16x16x32_bf16 v[76:79], v[206:209], v[190:193], v[76:79]
	v_mfma_f32_16x16x32_bf16 v[72:75], v[214:217], v[190:193], v[72:75]
	v_mfma_f32_16x16x32_bf16 v[68:71], v[206:209], v[198:201], v[68:71]
	v_mfma_f32_16x16x32_bf16 v[64:67], v[214:217], v[198:201], v[64:67]
	v_mfma_f32_16x16x32_bf16 v[92:95], v[210:213], v[178:181], v[92:95]
	v_mfma_f32_16x16x32_bf16 v[88:91], v[218:221], v[178:181], v[88:91]
	v_mfma_f32_16x16x32_bf16 v[84:87], v[210:213], v[186:189], v[84:87]
	v_mfma_f32_16x16x32_bf16 v[80:83], v[218:221], v[186:189], v[80:83]
	v_mfma_f32_16x16x32_bf16 v[76:79], v[210:213], v[194:197], v[76:79]
	v_mfma_f32_16x16x32_bf16 v[72:75], v[218:221], v[194:197], v[72:75]
	v_mfma_f32_16x16x32_bf16 v[68:71], v[210:213], v[202:205], v[68:71]
	v_mfma_f32_16x16x32_bf16 v[64:67], v[218:221], v[202:205], v[64:67]
	s_setprio 0
	s_mov_b32 m0, s61
	v_lshl_add_u64 v[222:223], v[226:227], 0, s[12:13]
	s_barrier
	ds_read_b128 v[166:169], v146 offset:49152
	ds_read_b128 v[178:181], v146 offset:50176
	ds_read_b128 v[182:185], v146 offset:51200
	ds_read_b128 v[186:189], v146 offset:52224
	ds_read_b128 v[190:193], v146 offset:53248
	ds_read_b128 v[194:197], v146 offset:54272
	ds_read_b128 v[198:201], v146 offset:55296
	ds_read_b128 v[202:205], v146 offset:56320
	global_load_lds_dwordx4 v[222:223], off
	v_lshl_add_u64 v[222:223], v[228:229], 0, s[12:13]
	s_mov_b32 m0, s62
	s_nop 0
	global_load_lds_dwordx4 v[222:223], off
	s_barrier
	s_waitcnt lgkmcnt(0)
	s_setprio 1
	s_waitcnt lgkmcnt(0)
	v_mfma_f32_16x16x32_bf16 v[60:63], v[150:153], v[166:169], v[60:63]
	v_mfma_f32_16x16x32_bf16 v[56:59], v[158:161], v[166:169], v[56:59]
	v_mfma_f32_16x16x32_bf16 v[52:55], v[150:153], v[182:185], v[52:55]
	v_mfma_f32_16x16x32_bf16 v[48:51], v[158:161], v[182:185], v[48:51]
	v_mfma_f32_16x16x32_bf16 v[44:47], v[150:153], v[190:193], v[44:47]
	v_mfma_f32_16x16x32_bf16 v[40:43], v[158:161], v[190:193], v[40:43]
	v_mfma_f32_16x16x32_bf16 v[36:39], v[150:153], v[198:201], v[36:39]
	v_mfma_f32_16x16x32_bf16 v[32:35], v[158:161], v[198:201], v[32:35]
	v_mfma_f32_16x16x32_bf16 v[60:63], v[154:157], v[178:181], v[60:63]
	v_mfma_f32_16x16x32_bf16 v[56:59], v[162:165], v[178:181], v[56:59]
	v_mfma_f32_16x16x32_bf16 v[52:55], v[154:157], v[186:189], v[52:55]
	v_mfma_f32_16x16x32_bf16 v[48:51], v[162:165], v[186:189], v[48:51]
	v_mfma_f32_16x16x32_bf16 v[44:47], v[154:157], v[194:197], v[44:47]
	v_mfma_f32_16x16x32_bf16 v[40:43], v[162:165], v[194:197], v[40:43]
	v_mfma_f32_16x16x32_bf16 v[36:39], v[154:157], v[202:205], v[36:39]
	v_mfma_f32_16x16x32_bf16 v[32:35], v[162:165], v[202:205], v[32:35]
	s_setprio 0
	s_barrier
	s_add_u32 s36, s36, 0x40080
	s_addc_u32 s37, s37, 0
	s_add_i32 s33, s40, s53
	v_lshl_add_u64 v[150:151], s[36:37], 0, v[130:131]
	s_mov_b32 m0, s33
	s_nop 0
	global_load_lds_dwordx4 v[150:151], off
	v_lshl_add_u64 v[150:151], s[36:37], 0, v[128:129]
	s_add_i32 m0, s33, 0x2000
	s_nop 0
	global_load_lds_dwordx4 v[150:151], off
	s_waitcnt vmcnt(6)
	s_barrier
	s_setprio 1
	v_mfma_f32_16x16x32_bf16 v[28:31], v[206:209], v[166:169], v[28:31]
	v_mfma_f32_16x16x32_bf16 v[24:27], v[214:217], v[166:169], v[24:27]
	v_mfma_f32_16x16x32_bf16 v[20:23], v[206:209], v[182:185], v[20:23]
	v_mfma_f32_16x16x32_bf16 v[16:19], v[214:217], v[182:185], v[16:19]
	v_mfma_f32_16x16x32_bf16 v[12:15], v[206:209], v[190:193], v[12:15]
	v_mfma_f32_16x16x32_bf16 v[8:11], v[214:217], v[190:193], v[8:11]
	v_mfma_f32_16x16x32_bf16 v[4:7], v[206:209], v[198:201], v[4:7]
	v_mfma_f32_16x16x32_bf16 v[0:3], v[214:217], v[198:201], v[0:3]
	v_mfma_f32_16x16x32_bf16 v[28:31], v[210:213], v[178:181], v[28:31]
	v_mfma_f32_16x16x32_bf16 v[24:27], v[218:221], v[178:181], v[24:27]
	v_mfma_f32_16x16x32_bf16 v[20:23], v[210:213], v[186:189], v[20:23]
	v_mfma_f32_16x16x32_bf16 v[16:19], v[218:221], v[186:189], v[16:19]
	v_mfma_f32_16x16x32_bf16 v[12:15], v[210:213], v[194:197], v[12:15]
	v_mfma_f32_16x16x32_bf16 v[8:11], v[218:221], v[194:197], v[8:11]
	v_mfma_f32_16x16x32_bf16 v[4:7], v[210:213], v[202:205], v[4:7]
	v_mfma_f32_16x16x32_bf16 v[0:3], v[218:221], v[202:205], v[0:3]
	s_setprio 0
	s_add_i32 s71, s71, 2
	s_add_u32 s69, s69, 0x100
	s_addc_u32 s70, s70, 0
	s_add_u32 s34, s34, 0x100
	s_addc_u32 s35, s35, 0
	s_cmp_gt_u32 s71, 13
	s_barrier
	s_cbranch_scc0 .LBB0_1396
	s_lshl_b32 s23, s30, 21
	s_lshl_b32 s25, s31, 17
	s_add_i32 s23, s23, s25
	s_lshl_b32 s25, s59, 7
	s_add_i32 s23, s23, s25
	s_lshr_b32 s25, s60, 6
	s_lshl_b32 s25, s25, 15
	s_add_i32 s23, s23, s25
	s_bfe_u32 s25, s60, 0x10005
	s_lshl_b32 s25, s25, 6
	s_add_i32 s23, s23, s25
	v_lshl_add_u32 v132, v142, 7, s23
	v_lshl_add_u32 v132, v144, 2, v132
	v_lshrrev_b32_e32 v152, 2, v144
	v_and_b32_e32 v149, 1, v152
	v_lshrrev_b32_e32 v150, 1, v152
	v_lshl_or_b32 v149, v149, 1, v150
	v_xor_b32_e32 v150, 2, v149
	v_lshl_add_u32 v149, v149, 4, v142
	v_lshl_add_u32 v150, v150, 4, v142
	v_lshlrev_b32_e32 v149, 2, v149
	v_lshlrev_b32_e32 v150, 2, v150
	v_and_b32_e32 v151, 4, v144
	v_cmp_ne_u32_e64 s[34:35], 0, v151
	v_cmp_lt_u32_e64 s[36:37], 4, v144
	v_max_f32_e32 v124, v124, v124
	v_max_f32_e32 v125, v125, v125
	v_max_f32_e32 v126, v126, v126
	v_max_f32_e32 v127, v127, v127
	v_max_f32_e32 v124, 0, v124
	v_max_f32_e32 v125, 0, v125
	v_max_f32_e32 v126, 0, v126
	v_max_f32_e32 v127, 0, v127
	v_pk_mul_f32 v[124:125], v[124:125], v[124:125]
	v_pk_mul_f32 v[126:127], v[126:127], v[126:127]
	v_cvt_pk_bf16_f32 v124, v124, v125
	v_cvt_pk_bf16_f32 v125, v126, v127
	v_max_f32_e32 v120, v120, v120
	v_max_f32_e32 v121, v121, v121
	v_max_f32_e32 v122, v122, v122
	v_max_f32_e32 v123, v123, v123
	v_max_f32_e32 v120, 0, v120
	v_max_f32_e32 v121, 0, v121
	v_max_f32_e32 v122, 0, v122
	v_max_f32_e32 v123, 0, v123
	v_pk_mul_f32 v[120:121], v[120:121], v[120:121]
	v_pk_mul_f32 v[122:123], v[122:123], v[122:123]
	v_cvt_pk_bf16_f32 v120, v120, v121
	v_cvt_pk_bf16_f32 v121, v122, v123
	v_cndmask_b32_e64 v126, v124, v120, s[34:35]
	v_cndmask_b32_e64 v127, v125, v121, s[34:35]
	v_cndmask_b32_e64 v122, v120, v124, s[34:35]
	v_cndmask_b32_e64 v123, v121, v125, s[34:35]
	ds_permute_b32 v124, v149, v126
	ds_permute_b32 v125, v149, v127
	ds_permute_b32 v120, v150, v122
	ds_permute_b32 v121, v150, v123
	v_max_f32_e32 v92, v92, v92
	v_max_f32_e32 v93, v93, v93
	v_max_f32_e32 v94, v94, v94
	v_max_f32_e32 v95, v95, v95
	v_max_f32_e32 v92, 0, v92
	v_max_f32_e32 v93, 0, v93
	v_max_f32_e32 v94, 0, v94
	v_max_f32_e32 v95, 0, v95
	v_pk_mul_f32 v[92:93], v[92:93], v[92:93]
	v_pk_mul_f32 v[94:95], v[94:95], v[94:95]
	v_cvt_pk_bf16_f32 v92, v92, v93
	v_cvt_pk_bf16_f32 v93, v94, v95
	v_max_f32_e32 v88, v88, v88
	v_max_f32_e32 v89, v89, v89
	v_max_f32_e32 v90, v90, v90
	v_max_f32_e32 v91, v91, v91
	v_max_f32_e32 v88, 0, v88
	v_max_f32_e32 v89, 0, v89
	v_max_f32_e32 v90, 0, v90
	v_max_f32_e32 v91, 0, v91
	v_pk_mul_f32 v[88:89], v[88:89], v[88:89]
	v_pk_mul_f32 v[90:91], v[90:91], v[90:91]
	v_cvt_pk_bf16_f32 v88, v88, v89
	v_cvt_pk_bf16_f32 v89, v90, v91
	v_cndmask_b32_e64 v94, v92, v88, s[34:35]
	v_cndmask_b32_e64 v95, v93, v89, s[34:35]
	v_cndmask_b32_e64 v90, v88, v92, s[34:35]
	v_cndmask_b32_e64 v91, v89, v93, s[34:35]
	ds_permute_b32 v92, v149, v94
	ds_permute_b32 v93, v149, v95
	ds_permute_b32 v88, v150, v90
	ds_permute_b32 v89, v150, v91
	s_waitcnt lgkmcnt(4)
	v_cndmask_b32_e64 v126, v120, v124, s[36:37]
	v_cndmask_b32_e64 v127, v121, v125, s[36:37]
	v_cndmask_b32_e64 v124, v124, v120, s[36:37]
	v_cndmask_b32_e64 v125, v125, v121, s[36:37]
	global_store_dwordx4 v132, v[124:127], s[16:17] nt
	v_max_f32_e32 v116, v116, v116
	v_max_f32_e32 v117, v117, v117
	v_max_f32_e32 v118, v118, v118
	v_max_f32_e32 v119, v119, v119
	v_max_f32_e32 v116, 0, v116
	v_max_f32_e32 v117, 0, v117
	v_max_f32_e32 v118, 0, v118
	v_max_f32_e32 v119, 0, v119
	v_pk_mul_f32 v[116:117], v[116:117], v[116:117]
	v_pk_mul_f32 v[118:119], v[118:119], v[118:119]
	v_cvt_pk_bf16_f32 v116, v116, v117
	v_cvt_pk_bf16_f32 v117, v118, v119
	v_max_f32_e32 v112, v112, v112
	v_max_f32_e32 v113, v113, v113
	v_max_f32_e32 v114, v114, v114
	v_max_f32_e32 v115, v115, v115
	v_max_f32_e32 v112, 0, v112
	v_max_f32_e32 v113, 0, v113
	v_max_f32_e32 v114, 0, v114
	v_max_f32_e32 v115, 0, v115
	v_pk_mul_f32 v[112:113], v[112:113], v[112:113]
	v_pk_mul_f32 v[114:115], v[114:115], v[114:115]
	v_cvt_pk_bf16_f32 v112, v112, v113
	v_cvt_pk_bf16_f32 v113, v114, v115
	v_cndmask_b32_e64 v118, v116, v112, s[34:35]
	v_cndmask_b32_e64 v119, v117, v113, s[34:35]
	v_cndmask_b32_e64 v114, v112, v116, s[34:35]
	v_cndmask_b32_e64 v115, v113, v117, s[34:35]
	ds_permute_b32 v116, v149, v118
	ds_permute_b32 v117, v149, v119
	ds_permute_b32 v112, v150, v114
	ds_permute_b32 v113, v150, v115
	s_waitcnt lgkmcnt(4)
	v_cndmask_b32_e64 v94, v88, v92, s[36:37]
	v_cndmask_b32_e64 v95, v89, v93, s[36:37]
	v_cndmask_b32_e64 v92, v92, v88, s[36:37]
	v_cndmask_b32_e64 v93, v93, v89, s[36:37]
	v_add_u32_e32 v151, 0x10000, v132
	global_store_dwordx4 v151, v[92:95], s[16:17] nt
	v_max_f32_e32 v84, v84, v84
	v_max_f32_e32 v85, v85, v85
	v_max_f32_e32 v86, v86, v86
	v_max_f32_e32 v87, v87, v87
	v_max_f32_e32 v84, 0, v84
	v_max_f32_e32 v85, 0, v85
	v_max_f32_e32 v86, 0, v86
	v_max_f32_e32 v87, 0, v87
	v_pk_mul_f32 v[84:85], v[84:85], v[84:85]
	v_pk_mul_f32 v[86:87], v[86:87], v[86:87]
	v_cvt_pk_bf16_f32 v84, v84, v85
	v_cvt_pk_bf16_f32 v85, v86, v87
	v_max_f32_e32 v80, v80, v80
	v_max_f32_e32 v81, v81, v81
	v_max_f32_e32 v82, v82, v82
	v_max_f32_e32 v83, v83, v83
	v_max_f32_e32 v80, 0, v80
	v_max_f32_e32 v81, 0, v81
	v_max_f32_e32 v82, 0, v82
	v_max_f32_e32 v83, 0, v83
	v_pk_mul_f32 v[80:81], v[80:81], v[80:81]
	v_pk_mul_f32 v[82:83], v[82:83], v[82:83]
	v_cvt_pk_bf16_f32 v80, v80, v81
	v_cvt_pk_bf16_f32 v81, v82, v83
	v_cndmask_b32_e64 v86, v84, v80, s[34:35]
	v_cndmask_b32_e64 v87, v85, v81, s[34:35]
	v_cndmask_b32_e64 v82, v80, v84, s[34:35]
	v_cndmask_b32_e64 v83, v81, v85, s[34:35]
	ds_permute_b32 v84, v149, v86
	ds_permute_b32 v85, v149, v87
	ds_permute_b32 v80, v150, v82
	ds_permute_b32 v81, v150, v83
	s_waitcnt lgkmcnt(4)
	v_cndmask_b32_e64 v118, v112, v116, s[36:37]
	v_cndmask_b32_e64 v119, v113, v117, s[36:37]
	v_cndmask_b32_e64 v116, v116, v112, s[36:37]
	v_cndmask_b32_e64 v117, v117, v113, s[36:37]
	v_add_u32_e32 v151, 0x800, v132
	global_store_dwordx4 v151, v[116:119], s[16:17] nt
	v_max_f32_e32 v108, v108, v108
	v_max_f32_e32 v109, v109, v109
	v_max_f32_e32 v110, v110, v110
	v_max_f32_e32 v111, v111, v111
	v_max_f32_e32 v108, 0, v108
	v_max_f32_e32 v109, 0, v109
	v_max_f32_e32 v110, 0, v110
	v_max_f32_e32 v111, 0, v111
	v_pk_mul_f32 v[108:109], v[108:109], v[108:109]
	v_pk_mul_f32 v[110:111], v[110:111], v[110:111]
	v_cvt_pk_bf16_f32 v108, v108, v109
	v_cvt_pk_bf16_f32 v109, v110, v111
	v_max_f32_e32 v104, v104, v104
	v_max_f32_e32 v105, v105, v105
	v_max_f32_e32 v106, v106, v106
	v_max_f32_e32 v107, v107, v107
	v_max_f32_e32 v104, 0, v104
	v_max_f32_e32 v105, 0, v105
	v_max_f32_e32 v106, 0, v106
	v_max_f32_e32 v107, 0, v107
	v_pk_mul_f32 v[104:105], v[104:105], v[104:105]
	v_pk_mul_f32 v[106:107], v[106:107], v[106:107]
	v_cvt_pk_bf16_f32 v104, v104, v105
	v_cvt_pk_bf16_f32 v105, v106, v107
	v_cndmask_b32_e64 v110, v108, v104, s[34:35]
	v_cndmask_b32_e64 v111, v109, v105, s[34:35]
	v_cndmask_b32_e64 v106, v104, v108, s[34:35]
	v_cndmask_b32_e64 v107, v105, v109, s[34:35]
	ds_permute_b32 v108, v149, v110
	ds_permute_b32 v109, v149, v111
	ds_permute_b32 v104, v150, v106
	ds_permute_b32 v105, v150, v107
	s_waitcnt lgkmcnt(4)
	v_cndmask_b32_e64 v86, v80, v84, s[36:37]
	v_cndmask_b32_e64 v87, v81, v85, s[36:37]
	v_cndmask_b32_e64 v84, v84, v80, s[36:37]
	v_cndmask_b32_e64 v85, v85, v81, s[36:37]
	v_add_u32_e32 v151, 0x10800, v132
	global_store_dwordx4 v151, v[84:87], s[16:17] nt
	v_max_f32_e32 v76, v76, v76
	v_max_f32_e32 v77, v77, v77
	v_max_f32_e32 v78, v78, v78
	v_max_f32_e32 v79, v79, v79
	v_max_f32_e32 v76, 0, v76
	v_max_f32_e32 v77, 0, v77
	v_max_f32_e32 v78, 0, v78
	v_max_f32_e32 v79, 0, v79
	v_pk_mul_f32 v[76:77], v[76:77], v[76:77]
	v_pk_mul_f32 v[78:79], v[78:79], v[78:79]
	v_cvt_pk_bf16_f32 v76, v76, v77
	v_cvt_pk_bf16_f32 v77, v78, v79
	v_max_f32_e32 v72, v72, v72
	v_max_f32_e32 v73, v73, v73
	v_max_f32_e32 v74, v74, v74
	v_max_f32_e32 v75, v75, v75
	v_max_f32_e32 v72, 0, v72
	v_max_f32_e32 v73, 0, v73
	v_max_f32_e32 v74, 0, v74
	v_max_f32_e32 v75, 0, v75
	v_pk_mul_f32 v[72:73], v[72:73], v[72:73]
	v_pk_mul_f32 v[74:75], v[74:75], v[74:75]
	v_cvt_pk_bf16_f32 v72, v72, v73
	v_cvt_pk_bf16_f32 v73, v74, v75
	v_cndmask_b32_e64 v78, v76, v72, s[34:35]
	v_cndmask_b32_e64 v79, v77, v73, s[34:35]
	v_cndmask_b32_e64 v74, v72, v76, s[34:35]
	v_cndmask_b32_e64 v75, v73, v77, s[34:35]
	ds_permute_b32 v76, v149, v78
	ds_permute_b32 v77, v149, v79
	ds_permute_b32 v72, v150, v74
	ds_permute_b32 v73, v150, v75
	s_waitcnt lgkmcnt(4)
	v_cndmask_b32_e64 v110, v104, v108, s[36:37]
	v_cndmask_b32_e64 v111, v105, v109, s[36:37]
	v_cndmask_b32_e64 v108, v108, v104, s[36:37]
	v_cndmask_b32_e64 v109, v109, v105, s[36:37]
	v_add_u32_e32 v151, 0x1000, v132
	global_store_dwordx4 v151, v[108:111], s[16:17] nt
	v_max_f32_e32 v100, v100, v100
	v_max_f32_e32 v101, v101, v101
	v_max_f32_e32 v102, v102, v102
	v_max_f32_e32 v103, v103, v103
	v_max_f32_e32 v100, 0, v100
	v_max_f32_e32 v101, 0, v101
	v_max_f32_e32 v102, 0, v102
	v_max_f32_e32 v103, 0, v103
	v_pk_mul_f32 v[100:101], v[100:101], v[100:101]
	v_pk_mul_f32 v[102:103], v[102:103], v[102:103]
	v_cvt_pk_bf16_f32 v100, v100, v101
	v_cvt_pk_bf16_f32 v101, v102, v103
	v_max_f32_e32 v96, v96, v96
	v_max_f32_e32 v97, v97, v97
	v_max_f32_e32 v98, v98, v98
	v_max_f32_e32 v99, v99, v99
	v_max_f32_e32 v96, 0, v96
	v_max_f32_e32 v97, 0, v97
	v_max_f32_e32 v98, 0, v98
	v_max_f32_e32 v99, 0, v99
	v_pk_mul_f32 v[96:97], v[96:97], v[96:97]
	v_pk_mul_f32 v[98:99], v[98:99], v[98:99]
	v_cvt_pk_bf16_f32 v96, v96, v97
	v_cvt_pk_bf16_f32 v97, v98, v99
	v_cndmask_b32_e64 v102, v100, v96, s[34:35]
	v_cndmask_b32_e64 v103, v101, v97, s[34:35]
	v_cndmask_b32_e64 v98, v96, v100, s[34:35]
	v_cndmask_b32_e64 v99, v97, v101, s[34:35]
	ds_permute_b32 v100, v149, v102
	ds_permute_b32 v101, v149, v103
	ds_permute_b32 v96, v150, v98
	ds_permute_b32 v97, v150, v99
	s_waitcnt lgkmcnt(4)
	v_cndmask_b32_e64 v78, v72, v76, s[36:37]
	v_cndmask_b32_e64 v79, v73, v77, s[36:37]
	v_cndmask_b32_e64 v76, v76, v72, s[36:37]
	v_cndmask_b32_e64 v77, v77, v73, s[36:37]
	v_add_u32_e32 v151, 0x11000, v132
	global_store_dwordx4 v151, v[76:79], s[16:17] nt
	v_max_f32_e32 v68, v68, v68
	v_max_f32_e32 v69, v69, v69
	v_max_f32_e32 v70, v70, v70
	v_max_f32_e32 v71, v71, v71
	v_max_f32_e32 v68, 0, v68
	v_max_f32_e32 v69, 0, v69
	v_max_f32_e32 v70, 0, v70
	v_max_f32_e32 v71, 0, v71
	v_pk_mul_f32 v[68:69], v[68:69], v[68:69]
	v_pk_mul_f32 v[70:71], v[70:71], v[70:71]
	v_cvt_pk_bf16_f32 v68, v68, v69
	v_cvt_pk_bf16_f32 v69, v70, v71
	v_max_f32_e32 v64, v64, v64
	v_max_f32_e32 v65, v65, v65
	v_max_f32_e32 v66, v66, v66
	v_max_f32_e32 v67, v67, v67
	v_max_f32_e32 v64, 0, v64
	v_max_f32_e32 v65, 0, v65
	v_max_f32_e32 v66, 0, v66
	v_max_f32_e32 v67, 0, v67
	v_pk_mul_f32 v[64:65], v[64:65], v[64:65]
	v_pk_mul_f32 v[66:67], v[66:67], v[66:67]
	v_cvt_pk_bf16_f32 v64, v64, v65
	v_cvt_pk_bf16_f32 v65, v66, v67
	v_cndmask_b32_e64 v70, v68, v64, s[34:35]
	v_cndmask_b32_e64 v71, v69, v65, s[34:35]
	v_cndmask_b32_e64 v66, v64, v68, s[34:35]
	v_cndmask_b32_e64 v67, v65, v69, s[34:35]
	ds_permute_b32 v68, v149, v70
	ds_permute_b32 v69, v149, v71
	ds_permute_b32 v64, v150, v66
	ds_permute_b32 v65, v150, v67
	s_waitcnt lgkmcnt(4)
	v_cndmask_b32_e64 v102, v96, v100, s[36:37]
	v_cndmask_b32_e64 v103, v97, v101, s[36:37]
	v_cndmask_b32_e64 v100, v100, v96, s[36:37]
	v_cndmask_b32_e64 v101, v101, v97, s[36:37]
	v_add_u32_e32 v151, 0x1800, v132
	global_store_dwordx4 v151, v[100:103], s[16:17] nt
	v_max_f32_e32 v60, v60, v60
	v_max_f32_e32 v61, v61, v61
	v_max_f32_e32 v62, v62, v62
	v_max_f32_e32 v63, v63, v63
	v_max_f32_e32 v60, 0, v60
	v_max_f32_e32 v61, 0, v61
	v_max_f32_e32 v62, 0, v62
	v_max_f32_e32 v63, 0, v63
	v_pk_mul_f32 v[60:61], v[60:61], v[60:61]
	v_pk_mul_f32 v[62:63], v[62:63], v[62:63]
	v_cvt_pk_bf16_f32 v60, v60, v61
	v_cvt_pk_bf16_f32 v61, v62, v63
	v_max_f32_e32 v56, v56, v56
	v_max_f32_e32 v57, v57, v57
	v_max_f32_e32 v58, v58, v58
	v_max_f32_e32 v59, v59, v59
	v_max_f32_e32 v56, 0, v56
	v_max_f32_e32 v57, 0, v57
	v_max_f32_e32 v58, 0, v58
	v_max_f32_e32 v59, 0, v59
	v_pk_mul_f32 v[56:57], v[56:57], v[56:57]
	v_pk_mul_f32 v[58:59], v[58:59], v[58:59]
	v_cvt_pk_bf16_f32 v56, v56, v57
	v_cvt_pk_bf16_f32 v57, v58, v59
	v_cndmask_b32_e64 v62, v60, v56, s[34:35]
	v_cndmask_b32_e64 v63, v61, v57, s[34:35]
	v_cndmask_b32_e64 v58, v56, v60, s[34:35]
	v_cndmask_b32_e64 v59, v57, v61, s[34:35]
	ds_permute_b32 v60, v149, v62
	ds_permute_b32 v61, v149, v63
	ds_permute_b32 v56, v150, v58
	ds_permute_b32 v57, v150, v59
	s_waitcnt lgkmcnt(4)
	v_cndmask_b32_e64 v70, v64, v68, s[36:37]
	v_cndmask_b32_e64 v71, v65, v69, s[36:37]
	v_cndmask_b32_e64 v68, v68, v64, s[36:37]
	v_cndmask_b32_e64 v69, v69, v65, s[36:37]
	v_add_u32_e32 v151, 0x11800, v132
	global_store_dwordx4 v151, v[68:71], s[16:17] nt
	v_max_f32_e32 v28, v28, v28
	v_max_f32_e32 v29, v29, v29
	v_max_f32_e32 v30, v30, v30
	v_max_f32_e32 v31, v31, v31
	v_max_f32_e32 v28, 0, v28
	v_max_f32_e32 v29, 0, v29
	v_max_f32_e32 v30, 0, v30
	v_max_f32_e32 v31, 0, v31
	v_pk_mul_f32 v[28:29], v[28:29], v[28:29]
	v_pk_mul_f32 v[30:31], v[30:31], v[30:31]
	v_cvt_pk_bf16_f32 v28, v28, v29
	v_cvt_pk_bf16_f32 v29, v30, v31
	v_max_f32_e32 v24, v24, v24
	v_max_f32_e32 v25, v25, v25
	v_max_f32_e32 v26, v26, v26
	v_max_f32_e32 v27, v27, v27
	v_max_f32_e32 v24, 0, v24
	v_max_f32_e32 v25, 0, v25
	v_max_f32_e32 v26, 0, v26
	v_max_f32_e32 v27, 0, v27
	v_pk_mul_f32 v[24:25], v[24:25], v[24:25]
	v_pk_mul_f32 v[26:27], v[26:27], v[26:27]
	v_cvt_pk_bf16_f32 v24, v24, v25
	v_cvt_pk_bf16_f32 v25, v26, v27
	v_cndmask_b32_e64 v30, v28, v24, s[34:35]
	v_cndmask_b32_e64 v31, v29, v25, s[34:35]
	v_cndmask_b32_e64 v26, v24, v28, s[34:35]
	v_cndmask_b32_e64 v27, v25, v29, s[34:35]
	ds_permute_b32 v28, v149, v30
	ds_permute_b32 v29, v149, v31
	ds_permute_b32 v24, v150, v26
	ds_permute_b32 v25, v150, v27
	s_waitcnt lgkmcnt(4)
	v_cndmask_b32_e64 v62, v56, v60, s[36:37]
	v_cndmask_b32_e64 v63, v57, v61, s[36:37]
	v_cndmask_b32_e64 v60, v60, v56, s[36:37]
	v_cndmask_b32_e64 v61, v61, v57, s[36:37]
	v_add_u32_e32 v151, 0x4000, v132
	global_store_dwordx4 v151, v[60:63], s[16:17] nt
	v_max_f32_e32 v52, v52, v52
	v_max_f32_e32 v53, v53, v53
	v_max_f32_e32 v54, v54, v54
	v_max_f32_e32 v55, v55, v55
	v_max_f32_e32 v52, 0, v52
	v_max_f32_e32 v53, 0, v53
	v_max_f32_e32 v54, 0, v54
	v_max_f32_e32 v55, 0, v55
	v_pk_mul_f32 v[52:53], v[52:53], v[52:53]
	v_pk_mul_f32 v[54:55], v[54:55], v[54:55]
	v_cvt_pk_bf16_f32 v52, v52, v53
	v_cvt_pk_bf16_f32 v53, v54, v55
	v_max_f32_e32 v48, v48, v48
	v_max_f32_e32 v49, v49, v49
	v_max_f32_e32 v50, v50, v50
	v_max_f32_e32 v51, v51, v51
	v_max_f32_e32 v48, 0, v48
	v_max_f32_e32 v49, 0, v49
	v_max_f32_e32 v50, 0, v50
	v_max_f32_e32 v51, 0, v51
	v_pk_mul_f32 v[48:49], v[48:49], v[48:49]
	v_pk_mul_f32 v[50:51], v[50:51], v[50:51]
	v_cvt_pk_bf16_f32 v48, v48, v49
	v_cvt_pk_bf16_f32 v49, v50, v51
	v_cndmask_b32_e64 v54, v52, v48, s[34:35]
	v_cndmask_b32_e64 v55, v53, v49, s[34:35]
	v_cndmask_b32_e64 v50, v48, v52, s[34:35]
	v_cndmask_b32_e64 v51, v49, v53, s[34:35]
	ds_permute_b32 v52, v149, v54
	ds_permute_b32 v53, v149, v55
	ds_permute_b32 v48, v150, v50
	ds_permute_b32 v49, v150, v51
	s_waitcnt lgkmcnt(4)
	v_cndmask_b32_e64 v30, v24, v28, s[36:37]
	v_cndmask_b32_e64 v31, v25, v29, s[36:37]
	v_cndmask_b32_e64 v28, v28, v24, s[36:37]
	v_cndmask_b32_e64 v29, v29, v25, s[36:37]
	v_add_u32_e32 v151, 0x14000, v132
	global_store_dwordx4 v151, v[28:31], s[16:17] nt
	v_max_f32_e32 v20, v20, v20
	v_max_f32_e32 v21, v21, v21
	v_max_f32_e32 v22, v22, v22
	v_max_f32_e32 v23, v23, v23
	v_max_f32_e32 v20, 0, v20
	v_max_f32_e32 v21, 0, v21
	v_max_f32_e32 v22, 0, v22
	v_max_f32_e32 v23, 0, v23
	v_pk_mul_f32 v[20:21], v[20:21], v[20:21]
	v_pk_mul_f32 v[22:23], v[22:23], v[22:23]
	v_cvt_pk_bf16_f32 v20, v20, v21
	v_cvt_pk_bf16_f32 v21, v22, v23
	v_max_f32_e32 v16, v16, v16
	v_max_f32_e32 v17, v17, v17
	v_max_f32_e32 v18, v18, v18
	v_max_f32_e32 v19, v19, v19
	v_max_f32_e32 v16, 0, v16
	v_max_f32_e32 v17, 0, v17
	v_max_f32_e32 v18, 0, v18
	v_max_f32_e32 v19, 0, v19
	v_pk_mul_f32 v[16:17], v[16:17], v[16:17]
	v_pk_mul_f32 v[18:19], v[18:19], v[18:19]
	v_cvt_pk_bf16_f32 v16, v16, v17
	v_cvt_pk_bf16_f32 v17, v18, v19
	v_cndmask_b32_e64 v22, v20, v16, s[34:35]
	v_cndmask_b32_e64 v23, v21, v17, s[34:35]
	v_cndmask_b32_e64 v18, v16, v20, s[34:35]
	v_cndmask_b32_e64 v19, v17, v21, s[34:35]
	ds_permute_b32 v20, v149, v22
	ds_permute_b32 v21, v149, v23
	ds_permute_b32 v16, v150, v18
	ds_permute_b32 v17, v150, v19
	s_waitcnt lgkmcnt(4)
	v_cndmask_b32_e64 v54, v48, v52, s[36:37]
	v_cndmask_b32_e64 v55, v49, v53, s[36:37]
	v_cndmask_b32_e64 v52, v52, v48, s[36:37]
	v_cndmask_b32_e64 v53, v53, v49, s[36:37]
	v_add_u32_e32 v151, 0x4800, v132
	global_store_dwordx4 v151, v[52:55], s[16:17] nt
	v_max_f32_e32 v44, v44, v44
	v_max_f32_e32 v45, v45, v45
	v_max_f32_e32 v46, v46, v46
	v_max_f32_e32 v47, v47, v47
	v_max_f32_e32 v44, 0, v44
	v_max_f32_e32 v45, 0, v45
	v_max_f32_e32 v46, 0, v46
	v_max_f32_e32 v47, 0, v47
	v_pk_mul_f32 v[44:45], v[44:45], v[44:45]
	v_pk_mul_f32 v[46:47], v[46:47], v[46:47]
	v_cvt_pk_bf16_f32 v44, v44, v45
	v_cvt_pk_bf16_f32 v45, v46, v47
	v_max_f32_e32 v40, v40, v40
	v_max_f32_e32 v41, v41, v41
	v_max_f32_e32 v42, v42, v42
	v_max_f32_e32 v43, v43, v43
	v_max_f32_e32 v40, 0, v40
	v_max_f32_e32 v41, 0, v41
	v_max_f32_e32 v42, 0, v42
	v_max_f32_e32 v43, 0, v43
	v_pk_mul_f32 v[40:41], v[40:41], v[40:41]
	v_pk_mul_f32 v[42:43], v[42:43], v[42:43]
	v_cvt_pk_bf16_f32 v40, v40, v41
	v_cvt_pk_bf16_f32 v41, v42, v43
	v_cndmask_b32_e64 v46, v44, v40, s[34:35]
	v_cndmask_b32_e64 v47, v45, v41, s[34:35]
	v_cndmask_b32_e64 v42, v40, v44, s[34:35]
	v_cndmask_b32_e64 v43, v41, v45, s[34:35]
	ds_permute_b32 v44, v149, v46
	ds_permute_b32 v45, v149, v47
	ds_permute_b32 v40, v150, v42
	ds_permute_b32 v41, v150, v43
	s_waitcnt lgkmcnt(4)
	v_cndmask_b32_e64 v22, v16, v20, s[36:37]
	v_cndmask_b32_e64 v23, v17, v21, s[36:37]
	v_cndmask_b32_e64 v20, v20, v16, s[36:37]
	v_cndmask_b32_e64 v21, v21, v17, s[36:37]
	v_add_u32_e32 v151, 0x14800, v132
	global_store_dwordx4 v151, v[20:23], s[16:17] nt
	v_max_f32_e32 v12, v12, v12
	v_max_f32_e32 v13, v13, v13
	v_max_f32_e32 v14, v14, v14
	v_max_f32_e32 v15, v15, v15
	v_max_f32_e32 v12, 0, v12
	v_max_f32_e32 v13, 0, v13
	v_max_f32_e32 v14, 0, v14
	v_max_f32_e32 v15, 0, v15
	v_pk_mul_f32 v[12:13], v[12:13], v[12:13]
	v_pk_mul_f32 v[14:15], v[14:15], v[14:15]
	v_cvt_pk_bf16_f32 v12, v12, v13
	v_cvt_pk_bf16_f32 v13, v14, v15
	v_max_f32_e32 v8, v8, v8
	v_max_f32_e32 v9, v9, v9
	v_max_f32_e32 v10, v10, v10
	v_max_f32_e32 v11, v11, v11
	v_max_f32_e32 v8, 0, v8
	v_max_f32_e32 v9, 0, v9
	v_max_f32_e32 v10, 0, v10
	v_max_f32_e32 v11, 0, v11
	v_pk_mul_f32 v[8:9], v[8:9], v[8:9]
	v_pk_mul_f32 v[10:11], v[10:11], v[10:11]
	v_cvt_pk_bf16_f32 v8, v8, v9
	v_cvt_pk_bf16_f32 v9, v10, v11
	v_cndmask_b32_e64 v14, v12, v8, s[34:35]
	v_cndmask_b32_e64 v15, v13, v9, s[34:35]
	v_cndmask_b32_e64 v10, v8, v12, s[34:35]
	v_cndmask_b32_e64 v11, v9, v13, s[34:35]
	ds_permute_b32 v12, v149, v14
	ds_permute_b32 v13, v149, v15
	ds_permute_b32 v8, v150, v10
	ds_permute_b32 v9, v150, v11
	s_waitcnt lgkmcnt(4)
	v_cndmask_b32_e64 v46, v40, v44, s[36:37]
	v_cndmask_b32_e64 v47, v41, v45, s[36:37]
	v_cndmask_b32_e64 v44, v44, v40, s[36:37]
	v_cndmask_b32_e64 v45, v45, v41, s[36:37]
	v_add_u32_e32 v151, 0x5000, v132
	global_store_dwordx4 v151, v[44:47], s[16:17] nt
	v_max_f32_e32 v36, v36, v36
	v_max_f32_e32 v37, v37, v37
	v_max_f32_e32 v38, v38, v38
	v_max_f32_e32 v39, v39, v39
	v_max_f32_e32 v36, 0, v36
	v_max_f32_e32 v37, 0, v37
	v_max_f32_e32 v38, 0, v38
	v_max_f32_e32 v39, 0, v39
	v_pk_mul_f32 v[36:37], v[36:37], v[36:37]
	v_pk_mul_f32 v[38:39], v[38:39], v[38:39]
	v_cvt_pk_bf16_f32 v36, v36, v37
	v_cvt_pk_bf16_f32 v37, v38, v39
	v_max_f32_e32 v32, v32, v32
	v_max_f32_e32 v33, v33, v33
	v_max_f32_e32 v34, v34, v34
	v_max_f32_e32 v35, v35, v35
	v_max_f32_e32 v32, 0, v32
	v_max_f32_e32 v33, 0, v33
	v_max_f32_e32 v34, 0, v34
	v_max_f32_e32 v35, 0, v35
	v_pk_mul_f32 v[32:33], v[32:33], v[32:33]
	v_pk_mul_f32 v[34:35], v[34:35], v[34:35]
	v_cvt_pk_bf16_f32 v32, v32, v33
	v_cvt_pk_bf16_f32 v33, v34, v35
	v_cndmask_b32_e64 v38, v36, v32, s[34:35]
	v_cndmask_b32_e64 v39, v37, v33, s[34:35]
	v_cndmask_b32_e64 v34, v32, v36, s[34:35]
	v_cndmask_b32_e64 v35, v33, v37, s[34:35]
	ds_permute_b32 v36, v149, v38
	ds_permute_b32 v37, v149, v39
	ds_permute_b32 v32, v150, v34
	ds_permute_b32 v33, v150, v35
	s_waitcnt lgkmcnt(4)
	v_cndmask_b32_e64 v14, v8, v12, s[36:37]
	v_cndmask_b32_e64 v15, v9, v13, s[36:37]
	v_cndmask_b32_e64 v12, v12, v8, s[36:37]
	v_cndmask_b32_e64 v13, v13, v9, s[36:37]
	v_add_u32_e32 v151, 0x15000, v132
	global_store_dwordx4 v151, v[12:15], s[16:17] nt
	v_max_f32_e32 v4, v4, v4
	v_max_f32_e32 v5, v5, v5
	v_max_f32_e32 v6, v6, v6
	v_max_f32_e32 v7, v7, v7
	v_max_f32_e32 v4, 0, v4
	v_max_f32_e32 v5, 0, v5
	v_max_f32_e32 v6, 0, v6
	v_max_f32_e32 v7, 0, v7
	v_pk_mul_f32 v[4:5], v[4:5], v[4:5]
	v_pk_mul_f32 v[6:7], v[6:7], v[6:7]
	v_cvt_pk_bf16_f32 v4, v4, v5
	v_cvt_pk_bf16_f32 v5, v6, v7
	v_max_f32_e32 v0, v0, v0
	v_max_f32_e32 v1, v1, v1
	v_max_f32_e32 v2, v2, v2
	v_max_f32_e32 v3, v3, v3
	v_max_f32_e32 v0, 0, v0
	v_max_f32_e32 v1, 0, v1
	v_max_f32_e32 v2, 0, v2
	v_max_f32_e32 v3, 0, v3
	v_pk_mul_f32 v[0:1], v[0:1], v[0:1]
	v_pk_mul_f32 v[2:3], v[2:3], v[2:3]
	v_cvt_pk_bf16_f32 v0, v0, v1
	v_cvt_pk_bf16_f32 v1, v2, v3
	v_cndmask_b32_e64 v6, v4, v0, s[34:35]
	v_cndmask_b32_e64 v7, v5, v1, s[34:35]
	v_cndmask_b32_e64 v2, v0, v4, s[34:35]
	v_cndmask_b32_e64 v3, v1, v5, s[34:35]
	ds_permute_b32 v4, v149, v6
	ds_permute_b32 v5, v149, v7
	ds_permute_b32 v0, v150, v2
	ds_permute_b32 v1, v150, v3
	s_waitcnt lgkmcnt(4)
	v_cndmask_b32_e64 v38, v32, v36, s[36:37]
	v_cndmask_b32_e64 v39, v33, v37, s[36:37]
	v_cndmask_b32_e64 v36, v36, v32, s[36:37]
	v_cndmask_b32_e64 v37, v37, v33, s[36:37]
	v_add_u32_e32 v151, 0x5800, v132
	global_store_dwordx4 v151, v[36:39], s[16:17] nt
	s_waitcnt lgkmcnt(0)
	v_cndmask_b32_e64 v6, v0, v4, s[36:37]
	v_cndmask_b32_e64 v7, v1, v5, s[36:37]
	v_cndmask_b32_e64 v4, v4, v0, s[36:37]
	v_cndmask_b32_e64 v5, v5, v1, s[36:37]
	v_add_u32_e32 v151, 0x15800, v132
	global_store_dwordx4 v151, v[4:7], s[16:17] nt
	s_and_b64 vcc, exec, s[10:11]
	s_mov_b32 s31, s22
	s_mov_b32 s30, s24
	s_mov_b64 s[34:35], s[28:29]
	s_mov_b64 s[36:37], s[26:27]
	s_cbranch_vccz .LBB0_1393
	s_waitcnt vmcnt(0)
	s_cmpk_gt_u32 s45, 0xff
	s_cbranch_scc1 .LBB0_1400
	s_barrier

.LBB0_1985:
	ds_read_b128 v[150:153], v145
	ds_read_b128 v[154:157], v145 offset:1024
	ds_read_b128 v[158:161], v145 offset:2048
	ds_read_b128 v[162:165], v145 offset:3072
	s_add_u32 s33, s30, 0xfffc0080
	s_addc_u32 s34, s31, -1
	s_cmp_eq_u32 s69, 12
	s_cselect_b32 s37, s23, s34
	s_cselect_b32 s36, s65, s33
	s_cselect_b32 s35, s21, s68
	s_cselect_b32 s34, s66, s67
	v_lshl_add_u64 v[206:207], s[30:31], 0, v[136:137]
	s_add_i32 m0, s52, 0xc000
	ds_read_b128 v[166:169], v146
	ds_read_b128 v[178:181], v146 offset:1024
	ds_read_b128 v[182:185], v146 offset:2048
	ds_read_b128 v[186:189], v146 offset:3072
	ds_read_b128 v[190:193], v146 offset:4096
	ds_read_b128 v[194:197], v146 offset:5120
	ds_read_b128 v[198:201], v146 offset:6144
	ds_read_b128 v[202:205], v146 offset:7168
	global_load_lds_dwordx4 v[206:207], off
	v_lshl_add_u64 v[206:207], s[30:31], 0, v[134:135]
	s_add_i32 m0, s52, 0xe000
	s_nop 0
	global_load_lds_dwordx4 v[206:207], off
	s_waitcnt lgkmcnt(8)
	s_barrier
	s_waitcnt lgkmcnt(0)
	s_setprio 1
	s_waitcnt lgkmcnt(0)
	v_mfma_f32_16x16x32_bf16 v[124:127], v[150:153], v[166:169], v[124:127]
	v_mfma_f32_16x16x32_bf16 v[120:123], v[158:161], v[166:169], v[120:123]
	v_mfma_f32_16x16x32_bf16 v[116:119], v[150:153], v[182:185], v[116:119]
	v_mfma_f32_16x16x32_bf16 v[112:115], v[158:161], v[182:185], v[112:115]
	v_mfma_f32_16x16x32_bf16 v[108:111], v[150:153], v[190:193], v[108:111]
	v_mfma_f32_16x16x32_bf16 v[104:107], v[158:161], v[190:193], v[104:107]
	v_mfma_f32_16x16x32_bf16 v[100:103], v[150:153], v[198:201], v[100:103]
	v_mfma_f32_16x16x32_bf16 v[96:99], v[158:161], v[198:201], v[96:99]
	v_mfma_f32_16x16x32_bf16 v[124:127], v[154:157], v[178:181], v[124:127]
	v_mfma_f32_16x16x32_bf16 v[120:123], v[162:165], v[178:181], v[120:123]
	v_mfma_f32_16x16x32_bf16 v[116:119], v[154:157], v[186:189], v[116:119]
	v_mfma_f32_16x16x32_bf16 v[112:115], v[162:165], v[186:189], v[112:115]
	v_mfma_f32_16x16x32_bf16 v[108:111], v[154:157], v[194:197], v[108:111]
	v_mfma_f32_16x16x32_bf16 v[104:107], v[162:165], v[194:197], v[104:107]
	v_mfma_f32_16x16x32_bf16 v[100:103], v[154:157], v[202:205], v[100:103]
	v_mfma_f32_16x16x32_bf16 v[96:99], v[162:165], v[202:205], v[96:99]
	s_setprio 0
	s_barrier
	s_add_i32 s33, s63, s51
	v_lshl_add_u64 v[222:223], s[34:35], 0, v[130:131]
	s_mov_b32 m0, s33
	ds_read_b128 v[206:209], v147
	ds_read_b128 v[210:213], v147 offset:1024
	ds_read_b128 v[214:217], v147 offset:2048
	ds_read_b128 v[218:221], v147 offset:3072
	global_load_lds_dwordx4 v[222:223], off
	v_lshl_add_u64 v[224:225], s[34:35], 0, v[128:129]
	s_add_i32 m0, s33, 0x2000
	s_nop 0
	global_load_lds_dwordx4 v[224:225], off
	s_barrier
	s_waitcnt lgkmcnt(0)
	s_setprio 1
	s_waitcnt lgkmcnt(0)
	v_mfma_f32_16x16x32_bf16 v[92:95], v[206:209], v[166:169], v[92:95]
	v_mfma_f32_16x16x32_bf16 v[88:91], v[214:217], v[166:169], v[88:91]
	v_mfma_f32_16x16x32_bf16 v[84:87], v[206:209], v[182:185], v[84:87]
	v_mfma_f32_16x16x32_bf16 v[80:83], v[214:217], v[182:185], v[80:83]
	v_mfma_f32_16x16x32_bf16 v[76:79], v[206:209], v[190:193], v[76:79]
	v_mfma_f32_16x16x32_bf16 v[72:75], v[214:217], v[190:193], v[72:75]
	v_mfma_f32_16x16x32_bf16 v[68:71], v[206:209], v[198:201], v[68:71]
	v_mfma_f32_16x16x32_bf16 v[64:67], v[214:217], v[198:201], v[64:67]
	v_mfma_f32_16x16x32_bf16 v[92:95], v[210:213], v[178:181], v[92:95]
	v_mfma_f32_16x16x32_bf16 v[88:91], v[218:221], v[178:181], v[88:91]
	v_mfma_f32_16x16x32_bf16 v[84:87], v[210:213], v[186:189], v[84:87]
	v_mfma_f32_16x16x32_bf16 v[80:83], v[218:221], v[186:189], v[80:83]
	v_mfma_f32_16x16x32_bf16 v[76:79], v[210:213], v[194:197], v[76:79]
	v_mfma_f32_16x16x32_bf16 v[72:75], v[218:221], v[194:197], v[72:75]
	v_mfma_f32_16x16x32_bf16 v[68:71], v[210:213], v[202:205], v[68:71]
	v_mfma_f32_16x16x32_bf16 v[64:67], v[218:221], v[202:205], v[64:67]
	s_setprio 0
	s_mov_b32 m0, s52
	v_lshl_add_u64 v[226:227], s[36:37], 0, v[130:131]
	s_barrier
	ds_read_b128 v[166:169], v146 offset:16384
	ds_read_b128 v[178:181], v146 offset:17408
	ds_read_b128 v[182:185], v146 offset:18432
	ds_read_b128 v[186:189], v146 offset:19456
	ds_read_b128 v[190:193], v146 offset:20480
	ds_read_b128 v[194:197], v146 offset:21504
	ds_read_b128 v[198:201], v146 offset:22528
	ds_read_b128 v[202:205], v146 offset:23552
	global_load_lds_dwordx4 v[226:227], off
	v_lshl_add_u64 v[228:229], s[36:37], 0, v[128:129]
	s_mov_b32 m0, s53
	s_nop 0
	global_load_lds_dwordx4 v[228:229], off
	s_barrier
	s_waitcnt lgkmcnt(0)
	s_setprio 1
	s_waitcnt lgkmcnt(0)
	v_mfma_f32_16x16x32_bf16 v[60:63], v[150:153], v[166:169], v[60:63]
	v_mfma_f32_16x16x32_bf16 v[56:59], v[158:161], v[166:169], v[56:59]
	v_mfma_f32_16x16x32_bf16 v[52:55], v[150:153], v[182:185], v[52:55]
	v_mfma_f32_16x16x32_bf16 v[48:51], v[158:161], v[182:185], v[48:51]
	v_mfma_f32_16x16x32_bf16 v[44:47], v[150:153], v[190:193], v[44:47]
	v_mfma_f32_16x16x32_bf16 v[40:43], v[158:161], v[190:193], v[40:43]
	v_mfma_f32_16x16x32_bf16 v[36:39], v[150:153], v[198:201], v[36:39]
	v_mfma_f32_16x16x32_bf16 v[32:35], v[158:161], v[198:201], v[32:35]
	v_mfma_f32_16x16x32_bf16 v[60:63], v[154:157], v[178:181], v[60:63]
	v_mfma_f32_16x16x32_bf16 v[56:59], v[162:165], v[178:181], v[56:59]
	v_mfma_f32_16x16x32_bf16 v[52:55], v[154:157], v[186:189], v[52:55]
	v_mfma_f32_16x16x32_bf16 v[48:51], v[162:165], v[186:189], v[48:51]
	v_mfma_f32_16x16x32_bf16 v[44:47], v[154:157], v[194:197], v[44:47]
	v_mfma_f32_16x16x32_bf16 v[40:43], v[162:165], v[194:197], v[40:43]
	v_mfma_f32_16x16x32_bf16 v[36:39], v[154:157], v[202:205], v[36:39]
	v_mfma_f32_16x16x32_bf16 v[32:35], v[162:165], v[202:205], v[32:35]
	s_setprio 0
	s_barrier
	s_add_u32 s70, s34, 0x40000
	s_addc_u32 s71, s35, 0
	s_add_i32 s33, s64, s51
	v_lshl_add_u64 v[150:151], s[70:71], 0, v[130:131]
	s_mov_b32 m0, s33
	s_nop 0
	global_load_lds_dwordx4 v[150:151], off
	v_lshl_add_u64 v[150:151], s[70:71], 0, v[128:129]
	s_add_i32 m0, s33, 0x2000
	s_nop 0
	global_load_lds_dwordx4 v[150:151], off
	s_waitcnt vmcnt(6)
	s_barrier
	s_setprio 1
	v_mfma_f32_16x16x32_bf16 v[28:31], v[206:209], v[166:169], v[28:31]
	v_mfma_f32_16x16x32_bf16 v[24:27], v[214:217], v[166:169], v[24:27]
	v_mfma_f32_16x16x32_bf16 v[20:23], v[206:209], v[182:185], v[20:23]
	v_mfma_f32_16x16x32_bf16 v[16:19], v[214:217], v[182:185], v[16:19]
	v_mfma_f32_16x16x32_bf16 v[12:15], v[206:209], v[190:193], v[12:15]
	v_mfma_f32_16x16x32_bf16 v[8:11], v[214:217], v[190:193], v[8:11]
	v_mfma_f32_16x16x32_bf16 v[4:7], v[206:209], v[198:201], v[4:7]
	v_mfma_f32_16x16x32_bf16 v[0:3], v[214:217], v[198:201], v[0:3]
	v_mfma_f32_16x16x32_bf16 v[28:31], v[210:213], v[178:181], v[28:31]
	v_mfma_f32_16x16x32_bf16 v[24:27], v[218:221], v[178:181], v[24:27]
	v_mfma_f32_16x16x32_bf16 v[20:23], v[210:213], v[186:189], v[20:23]
	v_mfma_f32_16x16x32_bf16 v[16:19], v[218:221], v[186:189], v[16:19]
	v_mfma_f32_16x16x32_bf16 v[12:15], v[210:213], v[194:197], v[12:15]
	v_mfma_f32_16x16x32_bf16 v[8:11], v[218:221], v[194:197], v[8:11]
	v_mfma_f32_16x16x32_bf16 v[4:7], v[210:213], v[202:205], v[4:7]
	v_mfma_f32_16x16x32_bf16 v[0:3], v[218:221], v[202:205], v[0:3]
	s_setprio 0
	s_add_i32 s33, 0, 0x18000
	v_add_u32_e32 v132, s33, v143
	s_barrier
	ds_read_b128 v[150:153], v132
	ds_read_b128 v[154:157], v132 offset:1024
	ds_read_b128 v[158:161], v132 offset:2048
	ds_read_b128 v[162:165], v132 offset:3072
	s_add_u32 s36, s36, 0x40000
	s_addc_u32 s37, s37, 0
	s_mov_b32 m0, s54
	v_lshl_add_u64 v[206:207], s[36:37], 0, v[130:131]
	ds_read_b128 v[166:169], v146 offset:32768
	ds_read_b128 v[178:181], v146 offset:33792
	ds_read_b128 v[182:185], v146 offset:34816
	ds_read_b128 v[186:189], v146 offset:35840
	ds_read_b128 v[190:193], v146 offset:36864
	ds_read_b128 v[194:197], v146 offset:37888
	ds_read_b128 v[198:201], v146 offset:38912
	ds_read_b128 v[202:205], v146 offset:39936
	global_load_lds_dwordx4 v[206:207], off
	v_lshl_add_u64 v[206:207], s[36:37], 0, v[128:129]
	s_mov_b32 m0, s55
	s_nop 0
	global_load_lds_dwordx4 v[206:207], off
	s_waitcnt lgkmcnt(8)
	s_barrier
	s_waitcnt lgkmcnt(0)
	s_setprio 1
	s_waitcnt lgkmcnt(0)
	v_mfma_f32_16x16x32_bf16 v[124:127], v[150:153], v[166:169], v[124:127]
	v_mfma_f32_16x16x32_bf16 v[120:123], v[158:161], v[166:169], v[120:123]
	v_mfma_f32_16x16x32_bf16 v[116:119], v[150:153], v[182:185], v[116:119]
	v_mfma_f32_16x16x32_bf16 v[112:115], v[158:161], v[182:185], v[112:115]
	v_mfma_f32_16x16x32_bf16 v[108:111], v[150:153], v[190:193], v[108:111]
	v_mfma_f32_16x16x32_bf16 v[104:107], v[158:161], v[190:193], v[104:107]
	v_mfma_f32_16x16x32_bf16 v[100:103], v[150:153], v[198:201], v[100:103]
	v_mfma_f32_16x16x32_bf16 v[96:99], v[158:161], v[198:201], v[96:99]
	v_mfma_f32_16x16x32_bf16 v[124:127], v[154:157], v[178:181], v[124:127]
	v_mfma_f32_16x16x32_bf16 v[120:123], v[162:165], v[178:181], v[120:123]
	v_mfma_f32_16x16x32_bf16 v[116:119], v[154:157], v[186:189], v[116:119]
	v_mfma_f32_16x16x32_bf16 v[112:115], v[162:165], v[186:189], v[112:115]
	v_mfma_f32_16x16x32_bf16 v[108:111], v[154:157], v[194:197], v[108:111]
	v_mfma_f32_16x16x32_bf16 v[104:107], v[162:165], v[194:197], v[104:107]
	v_mfma_f32_16x16x32_bf16 v[100:103], v[154:157], v[202:205], v[100:103]
	v_mfma_f32_16x16x32_bf16 v[96:99], v[162:165], v[202:205], v[96:99]
	s_setprio 0
	s_barrier
	s_add_i32 s36, 0, 0x1c000
	s_add_i32 s33, s33, s51
	v_add_u32_e32 v132, s36, v143
	v_lshl_add_u64 v[222:223], v[222:223], 0, s[12:13]
	s_mov_b32 m0, s33
	ds_read_b128 v[206:209], v132
	ds_read_b128 v[210:213], v132 offset:1024
	ds_read_b128 v[214:217], v132 offset:2048
	ds_read_b128 v[218:221], v132 offset:3072
	global_load_lds_dwordx4 v[222:223], off
	v_lshl_add_u64 v[222:223], v[224:225], 0, s[12:13]
	s_add_i32 m0, s33, 0x2000
	s_nop 0
	global_load_lds_dwordx4 v[222:223], off
	s_barrier
	s_waitcnt lgkmcnt(0)
	s_setprio 1
	s_waitcnt lgkmcnt(0)
	v_mfma_f32_16x16x32_bf16 v[92:95], v[206:209], v[166:169], v[92:95]
	v_mfma_f32_16x16x32_bf16 v[88:91], v[214:217], v[166:169], v[88:91]
	v_mfma_f32_16x16x32_bf16 v[84:87], v[206:209], v[182:185], v[84:87]
	v_mfma_f32_16x16x32_bf16 v[80:83], v[214:217], v[182:185], v[80:83]
	v_mfma_f32_16x16x32_bf16 v[76:79], v[206:209], v[190:193], v[76:79]
	v_mfma_f32_16x16x32_bf16 v[72:75], v[214:217], v[190:193], v[72:75]
	v_mfma_f32_16x16x32_bf16 v[68:71], v[206:209], v[198:201], v[68:71]
	v_mfma_f32_16x16x32_bf16 v[64:67], v[214:217], v[198:201], v[64:67]
	v_mfma_f32_16x16x32_bf16 v[92:95], v[210:213], v[178:181], v[92:95]
	v_mfma_f32_16x16x32_bf16 v[88:91], v[218:221], v[178:181], v[88:91]
	v_mfma_f32_16x16x32_bf16 v[84:87], v[210:213], v[186:189], v[84:87]
	v_mfma_f32_16x16x32_bf16 v[80:83], v[218:221], v[186:189], v[80:83]
	v_mfma_f32_16x16x32_bf16 v[76:79], v[210:213], v[194:197], v[76:79]
	v_mfma_f32_16x16x32_bf16 v[72:75], v[218:221], v[194:197], v[72:75]
	v_mfma_f32_16x16x32_bf16 v[68:71], v[210:213], v[202:205], v[68:71]
	v_mfma_f32_16x16x32_bf16 v[64:67], v[218:221], v[202:205], v[64:67]
	s_setprio 0
	s_mov_b32 m0, s59
	v_lshl_add_u64 v[222:223], v[226:227], 0, s[12:13]
	s_barrier
	ds_read_b128 v[166:169], v146 offset:49152
	ds_read_b128 v[178:181], v146 offset:50176
	ds_read_b128 v[182:185], v146 offset:51200
	ds_read_b128 v[186:189], v146 offset:52224
	ds_read_b128 v[190:193], v146 offset:53248
	ds_read_b128 v[194:197], v146 offset:54272
	ds_read_b128 v[198:201], v146 offset:55296
	ds_read_b128 v[202:205], v146 offset:56320
	global_load_lds_dwordx4 v[222:223], off
	v_lshl_add_u64 v[222:223], v[228:229], 0, s[12:13]
	s_mov_b32 m0, s60
	s_nop 0
	global_load_lds_dwordx4 v[222:223], off
	s_barrier
	s_waitcnt lgkmcnt(0)
	s_setprio 1
	s_waitcnt lgkmcnt(0)
	v_mfma_f32_16x16x32_bf16 v[60:63], v[150:153], v[166:169], v[60:63]
	v_mfma_f32_16x16x32_bf16 v[56:59], v[158:161], v[166:169], v[56:59]
	v_mfma_f32_16x16x32_bf16 v[52:55], v[150:153], v[182:185], v[52:55]
	v_mfma_f32_16x16x32_bf16 v[48:51], v[158:161], v[182:185], v[48:51]
	v_mfma_f32_16x16x32_bf16 v[44:47], v[150:153], v[190:193], v[44:47]
	v_mfma_f32_16x16x32_bf16 v[40:43], v[158:161], v[190:193], v[40:43]
	v_mfma_f32_16x16x32_bf16 v[36:39], v[150:153], v[198:201], v[36:39]
	v_mfma_f32_16x16x32_bf16 v[32:35], v[158:161], v[198:201], v[32:35]
	v_mfma_f32_16x16x32_bf16 v[60:63], v[154:157], v[178:181], v[60:63]
	v_mfma_f32_16x16x32_bf16 v[56:59], v[162:165], v[178:181], v[56:59]
	v_mfma_f32_16x16x32_bf16 v[52:55], v[154:157], v[186:189], v[52:55]
	v_mfma_f32_16x16x32_bf16 v[48:51], v[162:165], v[186:189], v[48:51]
	v_mfma_f32_16x16x32_bf16 v[44:47], v[154:157], v[194:197], v[44:47]
	v_mfma_f32_16x16x32_bf16 v[40:43], v[162:165], v[194:197], v[40:43]
	v_mfma_f32_16x16x32_bf16 v[36:39], v[154:157], v[202:205], v[36:39]
	v_mfma_f32_16x16x32_bf16 v[32:35], v[162:165], v[202:205], v[32:35]
	s_setprio 0
	s_barrier
	s_add_u32 s34, s34, 0x40080
	s_addc_u32 s35, s35, 0
	s_add_i32 s33, s36, s51
	v_lshl_add_u64 v[150:151], s[34:35], 0, v[130:131]
	s_mov_b32 m0, s33
	s_nop 0
	global_load_lds_dwordx4 v[150:151], off
	v_lshl_add_u64 v[150:151], s[34:35], 0, v[128:129]
	s_add_i32 m0, s33, 0x2000
	s_nop 0
	global_load_lds_dwordx4 v[150:151], off
	s_waitcnt vmcnt(6)
	s_barrier
	s_setprio 1
	v_mfma_f32_16x16x32_bf16 v[28:31], v[206:209], v[166:169], v[28:31]
	v_mfma_f32_16x16x32_bf16 v[24:27], v[214:217], v[166:169], v[24:27]
	v_mfma_f32_16x16x32_bf16 v[20:23], v[206:209], v[182:185], v[20:23]
	v_mfma_f32_16x16x32_bf16 v[16:19], v[214:217], v[182:185], v[16:19]
	v_mfma_f32_16x16x32_bf16 v[12:15], v[206:209], v[190:193], v[12:15]
	v_mfma_f32_16x16x32_bf16 v[8:11], v[214:217], v[190:193], v[8:11]
	v_mfma_f32_16x16x32_bf16 v[4:7], v[206:209], v[198:201], v[4:7]
	v_mfma_f32_16x16x32_bf16 v[0:3], v[214:217], v[198:201], v[0:3]
	v_mfma_f32_16x16x32_bf16 v[28:31], v[210:213], v[178:181], v[28:31]
	v_mfma_f32_16x16x32_bf16 v[24:27], v[218:221], v[178:181], v[24:27]
	v_mfma_f32_16x16x32_bf16 v[20:23], v[210:213], v[186:189], v[20:23]
	v_mfma_f32_16x16x32_bf16 v[16:19], v[218:221], v[186:189], v[16:19]
	v_mfma_f32_16x16x32_bf16 v[12:15], v[210:213], v[194:197], v[12:15]
	v_mfma_f32_16x16x32_bf16 v[8:11], v[218:221], v[194:197], v[8:11]
	v_mfma_f32_16x16x32_bf16 v[4:7], v[210:213], v[202:205], v[4:7]
	v_mfma_f32_16x16x32_bf16 v[0:3], v[218:221], v[202:205], v[0:3]
	s_setprio 0
	s_add_i32 s69, s69, 2
	s_add_u32 s67, s67, 0x100
	s_addc_u32 s68, s68, 0
	s_add_u32 s30, s30, 0x100
	s_addc_u32 s31, s31, 0
	s_cmp_gt_u32 s69, 13
	s_barrier
	s_cbranch_scc0 .LBB0_1985
	s_lshl_b32 s21, s28, 21
	s_lshl_b32 s23, s29, 17
	s_add_i32 s21, s21, s23
	s_lshl_b32 s23, s57, 7
	s_add_i32 s21, s21, s23
	s_lshr_b32 s23, s58, 6
	s_lshl_b32 s23, s23, 15
	s_add_i32 s21, s21, s23
	s_bfe_u32 s23, s58, 0x10005
	s_lshl_b32 s23, s23, 6
	s_add_i32 s21, s21, s23
	v_lshl_add_u32 v132, v142, 7, s21
	v_lshl_add_u32 v132, v144, 2, v132
	v_lshrrev_b32_e32 v152, 2, v144
	v_and_b32_e32 v149, 1, v152
	v_lshrrev_b32_e32 v150, 1, v152
	v_lshl_or_b32 v149, v149, 1, v150
	v_xor_b32_e32 v150, 2, v149
	v_lshl_add_u32 v149, v149, 4, v142
	v_lshl_add_u32 v150, v150, 4, v142
	v_lshlrev_b32_e32 v149, 2, v149
	v_lshlrev_b32_e32 v150, 2, v150
	v_and_b32_e32 v151, 4, v144
	v_cmp_ne_u32_e64 s[30:31], 0, v151
	v_cmp_lt_u32_e64 s[34:35], 4, v144
	v_max_f32_e32 v124, v124, v124
	v_max_f32_e32 v125, v125, v125
	v_max_f32_e32 v126, v126, v126
	v_max_f32_e32 v127, v127, v127
	v_max_f32_e32 v124, 0, v124
	v_max_f32_e32 v125, 0, v125
	v_max_f32_e32 v126, 0, v126
	v_max_f32_e32 v127, 0, v127
	v_pk_mul_f32 v[124:125], v[124:125], v[124:125]
	v_pk_mul_f32 v[126:127], v[126:127], v[126:127]
	v_cvt_pk_bf16_f32 v124, v124, v125
	v_cvt_pk_bf16_f32 v125, v126, v127
	v_max_f32_e32 v120, v120, v120
	v_max_f32_e32 v121, v121, v121
	v_max_f32_e32 v122, v122, v122
	v_max_f32_e32 v123, v123, v123
	v_max_f32_e32 v120, 0, v120
	v_max_f32_e32 v121, 0, v121
	v_max_f32_e32 v122, 0, v122
	v_max_f32_e32 v123, 0, v123
	v_pk_mul_f32 v[120:121], v[120:121], v[120:121]
	v_pk_mul_f32 v[122:123], v[122:123], v[122:123]
	v_cvt_pk_bf16_f32 v120, v120, v121
	v_cvt_pk_bf16_f32 v121, v122, v123
	v_cndmask_b32_e64 v126, v124, v120, s[30:31]
	v_cndmask_b32_e64 v127, v125, v121, s[30:31]
	v_cndmask_b32_e64 v122, v120, v124, s[30:31]
	v_cndmask_b32_e64 v123, v121, v125, s[30:31]
	ds_permute_b32 v124, v149, v126
	ds_permute_b32 v125, v149, v127
	ds_permute_b32 v120, v150, v122
	ds_permute_b32 v121, v150, v123
	v_max_f32_e32 v92, v92, v92
	v_max_f32_e32 v93, v93, v93
	v_max_f32_e32 v94, v94, v94
	v_max_f32_e32 v95, v95, v95
	v_max_f32_e32 v92, 0, v92
	v_max_f32_e32 v93, 0, v93
	v_max_f32_e32 v94, 0, v94
	v_max_f32_e32 v95, 0, v95
	v_pk_mul_f32 v[92:93], v[92:93], v[92:93]
	v_pk_mul_f32 v[94:95], v[94:95], v[94:95]
	v_cvt_pk_bf16_f32 v92, v92, v93
	v_cvt_pk_bf16_f32 v93, v94, v95
	v_max_f32_e32 v88, v88, v88
	v_max_f32_e32 v89, v89, v89
	v_max_f32_e32 v90, v90, v90
	v_max_f32_e32 v91, v91, v91
	v_max_f32_e32 v88, 0, v88
	v_max_f32_e32 v89, 0, v89
	v_max_f32_e32 v90, 0, v90
	v_max_f32_e32 v91, 0, v91
	v_pk_mul_f32 v[88:89], v[88:89], v[88:89]
	v_pk_mul_f32 v[90:91], v[90:91], v[90:91]
	v_cvt_pk_bf16_f32 v88, v88, v89
	v_cvt_pk_bf16_f32 v89, v90, v91
	v_cndmask_b32_e64 v94, v92, v88, s[30:31]
	v_cndmask_b32_e64 v95, v93, v89, s[30:31]
	v_cndmask_b32_e64 v90, v88, v92, s[30:31]
	v_cndmask_b32_e64 v91, v89, v93, s[30:31]
	ds_permute_b32 v92, v149, v94
	ds_permute_b32 v93, v149, v95
	ds_permute_b32 v88, v150, v90
	ds_permute_b32 v89, v150, v91
	s_waitcnt lgkmcnt(4)
	v_cndmask_b32_e64 v126, v120, v124, s[34:35]
	v_cndmask_b32_e64 v127, v121, v125, s[34:35]
	v_cndmask_b32_e64 v124, v124, v120, s[34:35]
	v_cndmask_b32_e64 v125, v125, v121, s[34:35]
	global_store_dwordx4 v132, v[124:127], s[14:15] nt
	v_max_f32_e32 v116, v116, v116
	v_max_f32_e32 v117, v117, v117
	v_max_f32_e32 v118, v118, v118
	v_max_f32_e32 v119, v119, v119
	v_max_f32_e32 v116, 0, v116
	v_max_f32_e32 v117, 0, v117
	v_max_f32_e32 v118, 0, v118
	v_max_f32_e32 v119, 0, v119
	v_pk_mul_f32 v[116:117], v[116:117], v[116:117]
	v_pk_mul_f32 v[118:119], v[118:119], v[118:119]
	v_cvt_pk_bf16_f32 v116, v116, v117
	v_cvt_pk_bf16_f32 v117, v118, v119
	v_max_f32_e32 v112, v112, v112
	v_max_f32_e32 v113, v113, v113
	v_max_f32_e32 v114, v114, v114
	v_max_f32_e32 v115, v115, v115
	v_max_f32_e32 v112, 0, v112
	v_max_f32_e32 v113, 0, v113
	v_max_f32_e32 v114, 0, v114
	v_max_f32_e32 v115, 0, v115
	v_pk_mul_f32 v[112:113], v[112:113], v[112:113]
	v_pk_mul_f32 v[114:115], v[114:115], v[114:115]
	v_cvt_pk_bf16_f32 v112, v112, v113
	v_cvt_pk_bf16_f32 v113, v114, v115
	v_cndmask_b32_e64 v118, v116, v112, s[30:31]
	v_cndmask_b32_e64 v119, v117, v113, s[30:31]
	v_cndmask_b32_e64 v114, v112, v116, s[30:31]
	v_cndmask_b32_e64 v115, v113, v117, s[30:31]
	ds_permute_b32 v116, v149, v118
	ds_permute_b32 v117, v149, v119
	ds_permute_b32 v112, v150, v114
	ds_permute_b32 v113, v150, v115
	s_waitcnt lgkmcnt(4)
	v_cndmask_b32_e64 v94, v88, v92, s[34:35]
	v_cndmask_b32_e64 v95, v89, v93, s[34:35]
	v_cndmask_b32_e64 v92, v92, v88, s[34:35]
	v_cndmask_b32_e64 v93, v93, v89, s[34:35]
	v_add_u32_e32 v151, 0x10000, v132
	global_store_dwordx4 v151, v[92:95], s[14:15] nt
	v_max_f32_e32 v84, v84, v84
	v_max_f32_e32 v85, v85, v85
	v_max_f32_e32 v86, v86, v86
	v_max_f32_e32 v87, v87, v87
	v_max_f32_e32 v84, 0, v84
	v_max_f32_e32 v85, 0, v85
	v_max_f32_e32 v86, 0, v86
	v_max_f32_e32 v87, 0, v87
	v_pk_mul_f32 v[84:85], v[84:85], v[84:85]
	v_pk_mul_f32 v[86:87], v[86:87], v[86:87]
	v_cvt_pk_bf16_f32 v84, v84, v85
	v_cvt_pk_bf16_f32 v85, v86, v87
	v_max_f32_e32 v80, v80, v80
	v_max_f32_e32 v81, v81, v81
	v_max_f32_e32 v82, v82, v82
	v_max_f32_e32 v83, v83, v83
	v_max_f32_e32 v80, 0, v80
	v_max_f32_e32 v81, 0, v81
	v_max_f32_e32 v82, 0, v82
	v_max_f32_e32 v83, 0, v83
	v_pk_mul_f32 v[80:81], v[80:81], v[80:81]
	v_pk_mul_f32 v[82:83], v[82:83], v[82:83]
	v_cvt_pk_bf16_f32 v80, v80, v81
	v_cvt_pk_bf16_f32 v81, v82, v83
	v_cndmask_b32_e64 v86, v84, v80, s[30:31]
	v_cndmask_b32_e64 v87, v85, v81, s[30:31]
	v_cndmask_b32_e64 v82, v80, v84, s[30:31]
	v_cndmask_b32_e64 v83, v81, v85, s[30:31]
	ds_permute_b32 v84, v149, v86
	ds_permute_b32 v85, v149, v87
	ds_permute_b32 v80, v150, v82
	ds_permute_b32 v81, v150, v83
	s_waitcnt lgkmcnt(4)
	v_cndmask_b32_e64 v118, v112, v116, s[34:35]
	v_cndmask_b32_e64 v119, v113, v117, s[34:35]
	v_cndmask_b32_e64 v116, v116, v112, s[34:35]
	v_cndmask_b32_e64 v117, v117, v113, s[34:35]
	v_add_u32_e32 v151, 0x800, v132
	global_store_dwordx4 v151, v[116:119], s[14:15] nt
	v_max_f32_e32 v108, v108, v108
	v_max_f32_e32 v109, v109, v109
	v_max_f32_e32 v110, v110, v110
	v_max_f32_e32 v111, v111, v111
	v_max_f32_e32 v108, 0, v108
	v_max_f32_e32 v109, 0, v109
	v_max_f32_e32 v110, 0, v110
	v_max_f32_e32 v111, 0, v111
	v_pk_mul_f32 v[108:109], v[108:109], v[108:109]
	v_pk_mul_f32 v[110:111], v[110:111], v[110:111]
	v_cvt_pk_bf16_f32 v108, v108, v109
	v_cvt_pk_bf16_f32 v109, v110, v111
	v_max_f32_e32 v104, v104, v104
	v_max_f32_e32 v105, v105, v105
	v_max_f32_e32 v106, v106, v106
	v_max_f32_e32 v107, v107, v107
	v_max_f32_e32 v104, 0, v104
	v_max_f32_e32 v105, 0, v105
	v_max_f32_e32 v106, 0, v106
	v_max_f32_e32 v107, 0, v107
	v_pk_mul_f32 v[104:105], v[104:105], v[104:105]
	v_pk_mul_f32 v[106:107], v[106:107], v[106:107]
	v_cvt_pk_bf16_f32 v104, v104, v105
	v_cvt_pk_bf16_f32 v105, v106, v107
	v_cndmask_b32_e64 v110, v108, v104, s[30:31]
	v_cndmask_b32_e64 v111, v109, v105, s[30:31]
	v_cndmask_b32_e64 v106, v104, v108, s[30:31]
	v_cndmask_b32_e64 v107, v105, v109, s[30:31]
	ds_permute_b32 v108, v149, v110
	ds_permute_b32 v109, v149, v111
	ds_permute_b32 v104, v150, v106
	ds_permute_b32 v105, v150, v107
	s_waitcnt lgkmcnt(4)
	v_cndmask_b32_e64 v86, v80, v84, s[34:35]
	v_cndmask_b32_e64 v87, v81, v85, s[34:35]
	v_cndmask_b32_e64 v84, v84, v80, s[34:35]
	v_cndmask_b32_e64 v85, v85, v81, s[34:35]
	v_add_u32_e32 v151, 0x10800, v132
	global_store_dwordx4 v151, v[84:87], s[14:15] nt
	v_max_f32_e32 v76, v76, v76
	v_max_f32_e32 v77, v77, v77
	v_max_f32_e32 v78, v78, v78
	v_max_f32_e32 v79, v79, v79
	v_max_f32_e32 v76, 0, v76
	v_max_f32_e32 v77, 0, v77
	v_max_f32_e32 v78, 0, v78
	v_max_f32_e32 v79, 0, v79
	v_pk_mul_f32 v[76:77], v[76:77], v[76:77]
	v_pk_mul_f32 v[78:79], v[78:79], v[78:79]
	v_cvt_pk_bf16_f32 v76, v76, v77
	v_cvt_pk_bf16_f32 v77, v78, v79
	v_max_f32_e32 v72, v72, v72
	v_max_f32_e32 v73, v73, v73
	v_max_f32_e32 v74, v74, v74
	v_max_f32_e32 v75, v75, v75
	v_max_f32_e32 v72, 0, v72
	v_max_f32_e32 v73, 0, v73
	v_max_f32_e32 v74, 0, v74
	v_max_f32_e32 v75, 0, v75
	v_pk_mul_f32 v[72:73], v[72:73], v[72:73]
	v_pk_mul_f32 v[74:75], v[74:75], v[74:75]
	v_cvt_pk_bf16_f32 v72, v72, v73
	v_cvt_pk_bf16_f32 v73, v74, v75
	v_cndmask_b32_e64 v78, v76, v72, s[30:31]
	v_cndmask_b32_e64 v79, v77, v73, s[30:31]
	v_cndmask_b32_e64 v74, v72, v76, s[30:31]
	v_cndmask_b32_e64 v75, v73, v77, s[30:31]
	ds_permute_b32 v76, v149, v78
	ds_permute_b32 v77, v149, v79
	ds_permute_b32 v72, v150, v74
	ds_permute_b32 v73, v150, v75
	s_waitcnt lgkmcnt(4)
	v_cndmask_b32_e64 v110, v104, v108, s[34:35]
	v_cndmask_b32_e64 v111, v105, v109, s[34:35]
	v_cndmask_b32_e64 v108, v108, v104, s[34:35]
	v_cndmask_b32_e64 v109, v109, v105, s[34:35]
	v_add_u32_e32 v151, 0x1000, v132
	global_store_dwordx4 v151, v[108:111], s[14:15] nt
	v_max_f32_e32 v100, v100, v100
	v_max_f32_e32 v101, v101, v101
	v_max_f32_e32 v102, v102, v102
	v_max_f32_e32 v103, v103, v103
	v_max_f32_e32 v100, 0, v100
	v_max_f32_e32 v101, 0, v101
	v_max_f32_e32 v102, 0, v102
	v_max_f32_e32 v103, 0, v103
	v_pk_mul_f32 v[100:101], v[100:101], v[100:101]
	v_pk_mul_f32 v[102:103], v[102:103], v[102:103]
	v_cvt_pk_bf16_f32 v100, v100, v101
	v_cvt_pk_bf16_f32 v101, v102, v103
	v_max_f32_e32 v96, v96, v96
	v_max_f32_e32 v97, v97, v97
	v_max_f32_e32 v98, v98, v98
	v_max_f32_e32 v99, v99, v99
	v_max_f32_e32 v96, 0, v96
	v_max_f32_e32 v97, 0, v97
	v_max_f32_e32 v98, 0, v98
	v_max_f32_e32 v99, 0, v99
	v_pk_mul_f32 v[96:97], v[96:97], v[96:97]
	v_pk_mul_f32 v[98:99], v[98:99], v[98:99]
	v_cvt_pk_bf16_f32 v96, v96, v97
	v_cvt_pk_bf16_f32 v97, v98, v99
	v_cndmask_b32_e64 v102, v100, v96, s[30:31]
	v_cndmask_b32_e64 v103, v101, v97, s[30:31]
	v_cndmask_b32_e64 v98, v96, v100, s[30:31]
	v_cndmask_b32_e64 v99, v97, v101, s[30:31]
	ds_permute_b32 v100, v149, v102
	ds_permute_b32 v101, v149, v103
	ds_permute_b32 v96, v150, v98
	ds_permute_b32 v97, v150, v99
	s_waitcnt lgkmcnt(4)
	v_cndmask_b32_e64 v78, v72, v76, s[34:35]
	v_cndmask_b32_e64 v79, v73, v77, s[34:35]
	v_cndmask_b32_e64 v76, v76, v72, s[34:35]
	v_cndmask_b32_e64 v77, v77, v73, s[34:35]
	v_add_u32_e32 v151, 0x11000, v132
	global_store_dwordx4 v151, v[76:79], s[14:15] nt
	v_max_f32_e32 v68, v68, v68
	v_max_f32_e32 v69, v69, v69
	v_max_f32_e32 v70, v70, v70
	v_max_f32_e32 v71, v71, v71
	v_max_f32_e32 v68, 0, v68
	v_max_f32_e32 v69, 0, v69
	v_max_f32_e32 v70, 0, v70
	v_max_f32_e32 v71, 0, v71
	v_pk_mul_f32 v[68:69], v[68:69], v[68:69]
	v_pk_mul_f32 v[70:71], v[70:71], v[70:71]
	v_cvt_pk_bf16_f32 v68, v68, v69
	v_cvt_pk_bf16_f32 v69, v70, v71
	v_max_f32_e32 v64, v64, v64
	v_max_f32_e32 v65, v65, v65
	v_max_f32_e32 v66, v66, v66
	v_max_f32_e32 v67, v67, v67
	v_max_f32_e32 v64, 0, v64
	v_max_f32_e32 v65, 0, v65
	v_max_f32_e32 v66, 0, v66
	v_max_f32_e32 v67, 0, v67
	v_pk_mul_f32 v[64:65], v[64:65], v[64:65]
	v_pk_mul_f32 v[66:67], v[66:67], v[66:67]
	v_cvt_pk_bf16_f32 v64, v64, v65
	v_cvt_pk_bf16_f32 v65, v66, v67
	v_cndmask_b32_e64 v70, v68, v64, s[30:31]
	v_cndmask_b32_e64 v71, v69, v65, s[30:31]
	v_cndmask_b32_e64 v66, v64, v68, s[30:31]
	v_cndmask_b32_e64 v67, v65, v69, s[30:31]
	ds_permute_b32 v68, v149, v70
	ds_permute_b32 v69, v149, v71
	ds_permute_b32 v64, v150, v66
	ds_permute_b32 v65, v150, v67
	s_waitcnt lgkmcnt(4)
	v_cndmask_b32_e64 v102, v96, v100, s[34:35]
	v_cndmask_b32_e64 v103, v97, v101, s[34:35]
	v_cndmask_b32_e64 v100, v100, v96, s[34:35]
	v_cndmask_b32_e64 v101, v101, v97, s[34:35]
	v_add_u32_e32 v151, 0x1800, v132
	global_store_dwordx4 v151, v[100:103], s[14:15] nt
	v_max_f32_e32 v60, v60, v60
	v_max_f32_e32 v61, v61, v61
	v_max_f32_e32 v62, v62, v62
	v_max_f32_e32 v63, v63, v63
	v_max_f32_e32 v60, 0, v60
	v_max_f32_e32 v61, 0, v61
	v_max_f32_e32 v62, 0, v62
	v_max_f32_e32 v63, 0, v63
	v_pk_mul_f32 v[60:61], v[60:61], v[60:61]
	v_pk_mul_f32 v[62:63], v[62:63], v[62:63]
	v_cvt_pk_bf16_f32 v60, v60, v61
	v_cvt_pk_bf16_f32 v61, v62, v63
	v_max_f32_e32 v56, v56, v56
	v_max_f32_e32 v57, v57, v57
	v_max_f32_e32 v58, v58, v58
	v_max_f32_e32 v59, v59, v59
	v_max_f32_e32 v56, 0, v56
	v_max_f32_e32 v57, 0, v57
	v_max_f32_e32 v58, 0, v58
	v_max_f32_e32 v59, 0, v59
	v_pk_mul_f32 v[56:57], v[56:57], v[56:57]
	v_pk_mul_f32 v[58:59], v[58:59], v[58:59]
	v_cvt_pk_bf16_f32 v56, v56, v57
	v_cvt_pk_bf16_f32 v57, v58, v59
	v_cndmask_b32_e64 v62, v60, v56, s[30:31]
	v_cndmask_b32_e64 v63, v61, v57, s[30:31]
	v_cndmask_b32_e64 v58, v56, v60, s[30:31]
	v_cndmask_b32_e64 v59, v57, v61, s[30:31]
	ds_permute_b32 v60, v149, v62
	ds_permute_b32 v61, v149, v63
	ds_permute_b32 v56, v150, v58
	ds_permute_b32 v57, v150, v59
	s_waitcnt lgkmcnt(4)
	v_cndmask_b32_e64 v70, v64, v68, s[34:35]
	v_cndmask_b32_e64 v71, v65, v69, s[34:35]
	v_cndmask_b32_e64 v68, v68, v64, s[34:35]
	v_cndmask_b32_e64 v69, v69, v65, s[34:35]
	v_add_u32_e32 v151, 0x11800, v132
	global_store_dwordx4 v151, v[68:71], s[14:15] nt
	v_max_f32_e32 v28, v28, v28
	v_max_f32_e32 v29, v29, v29
	v_max_f32_e32 v30, v30, v30
	v_max_f32_e32 v31, v31, v31
	v_max_f32_e32 v28, 0, v28
	v_max_f32_e32 v29, 0, v29
	v_max_f32_e32 v30, 0, v30
	v_max_f32_e32 v31, 0, v31
	v_pk_mul_f32 v[28:29], v[28:29], v[28:29]
	v_pk_mul_f32 v[30:31], v[30:31], v[30:31]
	v_cvt_pk_bf16_f32 v28, v28, v29
	v_cvt_pk_bf16_f32 v29, v30, v31
	v_max_f32_e32 v24, v24, v24
	v_max_f32_e32 v25, v25, v25
	v_max_f32_e32 v26, v26, v26
	v_max_f32_e32 v27, v27, v27
	v_max_f32_e32 v24, 0, v24
	v_max_f32_e32 v25, 0, v25
	v_max_f32_e32 v26, 0, v26
	v_max_f32_e32 v27, 0, v27
	v_pk_mul_f32 v[24:25], v[24:25], v[24:25]
	v_pk_mul_f32 v[26:27], v[26:27], v[26:27]
	v_cvt_pk_bf16_f32 v24, v24, v25
	v_cvt_pk_bf16_f32 v25, v26, v27
	v_cndmask_b32_e64 v30, v28, v24, s[30:31]
	v_cndmask_b32_e64 v31, v29, v25, s[30:31]
	v_cndmask_b32_e64 v26, v24, v28, s[30:31]
	v_cndmask_b32_e64 v27, v25, v29, s[30:31]
	ds_permute_b32 v28, v149, v30
	ds_permute_b32 v29, v149, v31
	ds_permute_b32 v24, v150, v26
	ds_permute_b32 v25, v150, v27
	s_waitcnt lgkmcnt(4)
	v_cndmask_b32_e64 v62, v56, v60, s[34:35]
	v_cndmask_b32_e64 v63, v57, v61, s[34:35]
	v_cndmask_b32_e64 v60, v60, v56, s[34:35]
	v_cndmask_b32_e64 v61, v61, v57, s[34:35]
	v_add_u32_e32 v151, 0x4000, v132
	global_store_dwordx4 v151, v[60:63], s[14:15] nt
	v_max_f32_e32 v52, v52, v52
	v_max_f32_e32 v53, v53, v53
	v_max_f32_e32 v54, v54, v54
	v_max_f32_e32 v55, v55, v55
	v_max_f32_e32 v52, 0, v52
	v_max_f32_e32 v53, 0, v53
	v_max_f32_e32 v54, 0, v54
	v_max_f32_e32 v55, 0, v55
	v_pk_mul_f32 v[52:53], v[52:53], v[52:53]
	v_pk_mul_f32 v[54:55], v[54:55], v[54:55]
	v_cvt_pk_bf16_f32 v52, v52, v53
	v_cvt_pk_bf16_f32 v53, v54, v55
	v_max_f32_e32 v48, v48, v48
	v_max_f32_e32 v49, v49, v49
	v_max_f32_e32 v50, v50, v50
	v_max_f32_e32 v51, v51, v51
	v_max_f32_e32 v48, 0, v48
	v_max_f32_e32 v49, 0, v49
	v_max_f32_e32 v50, 0, v50
	v_max_f32_e32 v51, 0, v51
	v_pk_mul_f32 v[48:49], v[48:49], v[48:49]
	v_pk_mul_f32 v[50:51], v[50:51], v[50:51]
	v_cvt_pk_bf16_f32 v48, v48, v49
	v_cvt_pk_bf16_f32 v49, v50, v51
	v_cndmask_b32_e64 v54, v52, v48, s[30:31]
	v_cndmask_b32_e64 v55, v53, v49, s[30:31]
	v_cndmask_b32_e64 v50, v48, v52, s[30:31]
	v_cndmask_b32_e64 v51, v49, v53, s[30:31]
	ds_permute_b32 v52, v149, v54
	ds_permute_b32 v53, v149, v55
	ds_permute_b32 v48, v150, v50
	ds_permute_b32 v49, v150, v51
	s_waitcnt lgkmcnt(4)
	v_cndmask_b32_e64 v30, v24, v28, s[34:35]
	v_cndmask_b32_e64 v31, v25, v29, s[34:35]
	v_cndmask_b32_e64 v28, v28, v24, s[34:35]
	v_cndmask_b32_e64 v29, v29, v25, s[34:35]
	v_add_u32_e32 v151, 0x14000, v132
	global_store_dwordx4 v151, v[28:31], s[14:15] nt
	v_max_f32_e32 v20, v20, v20
	v_max_f32_e32 v21, v21, v21
	v_max_f32_e32 v22, v22, v22
	v_max_f32_e32 v23, v23, v23
	v_max_f32_e32 v20, 0, v20
	v_max_f32_e32 v21, 0, v21
	v_max_f32_e32 v22, 0, v22
	v_max_f32_e32 v23, 0, v23
	v_pk_mul_f32 v[20:21], v[20:21], v[20:21]
	v_pk_mul_f32 v[22:23], v[22:23], v[22:23]
	v_cvt_pk_bf16_f32 v20, v20, v21
	v_cvt_pk_bf16_f32 v21, v22, v23
	v_max_f32_e32 v16, v16, v16
	v_max_f32_e32 v17, v17, v17
	v_max_f32_e32 v18, v18, v18
	v_max_f32_e32 v19, v19, v19
	v_max_f32_e32 v16, 0, v16
	v_max_f32_e32 v17, 0, v17
	v_max_f32_e32 v18, 0, v18
	v_max_f32_e32 v19, 0, v19
	v_pk_mul_f32 v[16:17], v[16:17], v[16:17]
	v_pk_mul_f32 v[18:19], v[18:19], v[18:19]
	v_cvt_pk_bf16_f32 v16, v16, v17
	v_cvt_pk_bf16_f32 v17, v18, v19
	v_cndmask_b32_e64 v22, v20, v16, s[30:31]
	v_cndmask_b32_e64 v23, v21, v17, s[30:31]
	v_cndmask_b32_e64 v18, v16, v20, s[30:31]
	v_cndmask_b32_e64 v19, v17, v21, s[30:31]
	ds_permute_b32 v20, v149, v22
	ds_permute_b32 v21, v149, v23
	ds_permute_b32 v16, v150, v18
	ds_permute_b32 v17, v150, v19
	s_waitcnt lgkmcnt(4)
	v_cndmask_b32_e64 v54, v48, v52, s[34:35]
	v_cndmask_b32_e64 v55, v49, v53, s[34:35]
	v_cndmask_b32_e64 v52, v52, v48, s[34:35]
	v_cndmask_b32_e64 v53, v53, v49, s[34:35]
	v_add_u32_e32 v151, 0x4800, v132
	global_store_dwordx4 v151, v[52:55], s[14:15] nt
	v_max_f32_e32 v44, v44, v44
	v_max_f32_e32 v45, v45, v45
	v_max_f32_e32 v46, v46, v46
	v_max_f32_e32 v47, v47, v47
	v_max_f32_e32 v44, 0, v44
	v_max_f32_e32 v45, 0, v45
	v_max_f32_e32 v46, 0, v46
	v_max_f32_e32 v47, 0, v47
	v_pk_mul_f32 v[44:45], v[44:45], v[44:45]
	v_pk_mul_f32 v[46:47], v[46:47], v[46:47]
	v_cvt_pk_bf16_f32 v44, v44, v45
	v_cvt_pk_bf16_f32 v45, v46, v47
	v_max_f32_e32 v40, v40, v40
	v_max_f32_e32 v41, v41, v41
	v_max_f32_e32 v42, v42, v42
	v_max_f32_e32 v43, v43, v43
	v_max_f32_e32 v40, 0, v40
	v_max_f32_e32 v41, 0, v41
	v_max_f32_e32 v42, 0, v42
	v_max_f32_e32 v43, 0, v43
	v_pk_mul_f32 v[40:41], v[40:41], v[40:41]
	v_pk_mul_f32 v[42:43], v[42:43], v[42:43]
	v_cvt_pk_bf16_f32 v40, v40, v41
	v_cvt_pk_bf16_f32 v41, v42, v43
	v_cndmask_b32_e64 v46, v44, v40, s[30:31]
	v_cndmask_b32_e64 v47, v45, v41, s[30:31]
	v_cndmask_b32_e64 v42, v40, v44, s[30:31]
	v_cndmask_b32_e64 v43, v41, v45, s[30:31]
	ds_permute_b32 v44, v149, v46
	ds_permute_b32 v45, v149, v47
	ds_permute_b32 v40, v150, v42
	ds_permute_b32 v41, v150, v43
	s_waitcnt lgkmcnt(4)
	v_cndmask_b32_e64 v22, v16, v20, s[34:35]
	v_cndmask_b32_e64 v23, v17, v21, s[34:35]
	v_cndmask_b32_e64 v20, v20, v16, s[34:35]
	v_cndmask_b32_e64 v21, v21, v17, s[34:35]
	v_add_u32_e32 v151, 0x14800, v132
	global_store_dwordx4 v151, v[20:23], s[14:15] nt
	v_max_f32_e32 v12, v12, v12
	v_max_f32_e32 v13, v13, v13
	v_max_f32_e32 v14, v14, v14
	v_max_f32_e32 v15, v15, v15
	v_max_f32_e32 v12, 0, v12
	v_max_f32_e32 v13, 0, v13
	v_max_f32_e32 v14, 0, v14
	v_max_f32_e32 v15, 0, v15
	v_pk_mul_f32 v[12:13], v[12:13], v[12:13]
	v_pk_mul_f32 v[14:15], v[14:15], v[14:15]
	v_cvt_pk_bf16_f32 v12, v12, v13
	v_cvt_pk_bf16_f32 v13, v14, v15
	v_max_f32_e32 v8, v8, v8
	v_max_f32_e32 v9, v9, v9
	v_max_f32_e32 v10, v10, v10
	v_max_f32_e32 v11, v11, v11
	v_max_f32_e32 v8, 0, v8
	v_max_f32_e32 v9, 0, v9
	v_max_f32_e32 v10, 0, v10
	v_max_f32_e32 v11, 0, v11
	v_pk_mul_f32 v[8:9], v[8:9], v[8:9]
	v_pk_mul_f32 v[10:11], v[10:11], v[10:11]
	v_cvt_pk_bf16_f32 v8, v8, v9
	v_cvt_pk_bf16_f32 v9, v10, v11
	v_cndmask_b32_e64 v14, v12, v8, s[30:31]
	v_cndmask_b32_e64 v15, v13, v9, s[30:31]
	v_cndmask_b32_e64 v10, v8, v12, s[30:31]
	v_cndmask_b32_e64 v11, v9, v13, s[30:31]
	ds_permute_b32 v12, v149, v14
	ds_permute_b32 v13, v149, v15
	ds_permute_b32 v8, v150, v10
	ds_permute_b32 v9, v150, v11
	s_waitcnt lgkmcnt(4)
	v_cndmask_b32_e64 v46, v40, v44, s[34:35]
	v_cndmask_b32_e64 v47, v41, v45, s[34:35]
	v_cndmask_b32_e64 v44, v44, v40, s[34:35]
	v_cndmask_b32_e64 v45, v45, v41, s[34:35]
	v_add_u32_e32 v151, 0x5000, v132
	global_store_dwordx4 v151, v[44:47], s[14:15] nt
	v_max_f32_e32 v36, v36, v36
	v_max_f32_e32 v37, v37, v37
	v_max_f32_e32 v38, v38, v38
	v_max_f32_e32 v39, v39, v39
	v_max_f32_e32 v36, 0, v36
	v_max_f32_e32 v37, 0, v37
	v_max_f32_e32 v38, 0, v38
	v_max_f32_e32 v39, 0, v39
	v_pk_mul_f32 v[36:37], v[36:37], v[36:37]
	v_pk_mul_f32 v[38:39], v[38:39], v[38:39]
	v_cvt_pk_bf16_f32 v36, v36, v37
	v_cvt_pk_bf16_f32 v37, v38, v39
	v_max_f32_e32 v32, v32, v32
	v_max_f32_e32 v33, v33, v33
	v_max_f32_e32 v34, v34, v34
	v_max_f32_e32 v35, v35, v35
	v_max_f32_e32 v32, 0, v32
	v_max_f32_e32 v33, 0, v33
	v_max_f32_e32 v34, 0, v34
	v_max_f32_e32 v35, 0, v35
	v_pk_mul_f32 v[32:33], v[32:33], v[32:33]
	v_pk_mul_f32 v[34:35], v[34:35], v[34:35]
	v_cvt_pk_bf16_f32 v32, v32, v33
	v_cvt_pk_bf16_f32 v33, v34, v35
	v_cndmask_b32_e64 v38, v36, v32, s[30:31]
	v_cndmask_b32_e64 v39, v37, v33, s[30:31]
	v_cndmask_b32_e64 v34, v32, v36, s[30:31]
	v_cndmask_b32_e64 v35, v33, v37, s[30:31]
	ds_permute_b32 v36, v149, v38
	ds_permute_b32 v37, v149, v39
	ds_permute_b32 v32, v150, v34
	ds_permute_b32 v33, v150, v35
	s_waitcnt lgkmcnt(4)
	v_cndmask_b32_e64 v14, v8, v12, s[34:35]
	v_cndmask_b32_e64 v15, v9, v13, s[34:35]
	v_cndmask_b32_e64 v12, v12, v8, s[34:35]
	v_cndmask_b32_e64 v13, v13, v9, s[34:35]
	v_add_u32_e32 v151, 0x15000, v132
	global_store_dwordx4 v151, v[12:15], s[14:15] nt
	v_max_f32_e32 v4, v4, v4
	v_max_f32_e32 v5, v5, v5
	v_max_f32_e32 v6, v6, v6
	v_max_f32_e32 v7, v7, v7
	v_max_f32_e32 v4, 0, v4
	v_max_f32_e32 v5, 0, v5
	v_max_f32_e32 v6, 0, v6
	v_max_f32_e32 v7, 0, v7
	v_pk_mul_f32 v[4:5], v[4:5], v[4:5]
	v_pk_mul_f32 v[6:7], v[6:7], v[6:7]
	v_cvt_pk_bf16_f32 v4, v4, v5
	v_cvt_pk_bf16_f32 v5, v6, v7
	v_max_f32_e32 v0, v0, v0
	v_max_f32_e32 v1, v1, v1
	v_max_f32_e32 v2, v2, v2
	v_max_f32_e32 v3, v3, v3
	v_max_f32_e32 v0, 0, v0
	v_max_f32_e32 v1, 0, v1
	v_max_f32_e32 v2, 0, v2
	v_max_f32_e32 v3, 0, v3
	v_pk_mul_f32 v[0:1], v[0:1], v[0:1]
	v_pk_mul_f32 v[2:3], v[2:3], v[2:3]
	v_cvt_pk_bf16_f32 v0, v0, v1
	v_cvt_pk_bf16_f32 v1, v2, v3
	v_cndmask_b32_e64 v6, v4, v0, s[30:31]
	v_cndmask_b32_e64 v7, v5, v1, s[30:31]
	v_cndmask_b32_e64 v2, v0, v4, s[30:31]
	v_cndmask_b32_e64 v3, v1, v5, s[30:31]
	ds_permute_b32 v4, v149, v6
	ds_permute_b32 v5, v149, v7
	ds_permute_b32 v0, v150, v2
	ds_permute_b32 v1, v150, v3
	s_waitcnt lgkmcnt(4)
	v_cndmask_b32_e64 v38, v32, v36, s[34:35]
	v_cndmask_b32_e64 v39, v33, v37, s[34:35]
	v_cndmask_b32_e64 v36, v36, v32, s[34:35]
	v_cndmask_b32_e64 v37, v37, v33, s[34:35]
	v_add_u32_e32 v151, 0x5800, v132
	global_store_dwordx4 v151, v[36:39], s[14:15] nt
	s_waitcnt lgkmcnt(0)
	v_cndmask_b32_e64 v6, v0, v4, s[34:35]
	v_cndmask_b32_e64 v7, v1, v5, s[34:35]
	v_cndmask_b32_e64 v4, v4, v0, s[34:35]
	v_cndmask_b32_e64 v5, v5, v1, s[34:35]
	v_add_u32_e32 v151, 0x15800, v132
	global_store_dwordx4 v151, v[4:7], s[14:15] nt
	s_and_b64 vcc, exec, s[8:9]
	s_mov_b32 s29, s20
	s_mov_b32 s28, s22
	s_mov_b64 s[30:31], s[26:27]
	s_mov_b64 s[34:35], s[24:25]
	s_cbranch_vccz .LBB0_1982
	s_waitcnt vmcnt(0)
	s_cmpk_gt_u32 s40, 0xff
	s_cbranch_scc1 .LBB0_1989
	s_barrier
